# mixer C: K rows of a unit staged once in LDS (time-sharing the V staging region: K for QK, then V for PV) and read as MFMA fragments by ds_read_b128, instead of 16 per-wave K tile loads from global (L
# speedup vs baseline: 1.0192x; 1.0103x over previous
; __device__ __forceinline__ void seq_of(int row, int& s0, int& T) { if (row < MP) { s0 = row & ~2047; T = 2048; } else { s0 = MP + ((row - MP) & ~4095); T = 4096; } }
; __device__ __forceinline__ void c_prefetch(const bf16* P, int un, int tid, int wave, int fr, int fq, v4u (&vpre)[9], bf16x8& Q0, bf16x8& Q1, bf16x8 (&K)[8][2]) {
;     const int h = un / (M / 128), blk = un - h * (M / 128), row0 = blk * 128; int s0, T; seq_of(row0, s0, T);
;     const int rows = T >> 6, rf = (row0 - s0) >> 6;
;     int R0 = rf - 4; R0 = R0 < 0 ? 0 : R0; R0 = R0 > rows - 8 ? rows - 8 : R0;
; #pragma unroll
;     for (int i = 0; i < 9; ++i) { const int e = tid + i * NTHREADS, key = e >> 3, chunk = e & 7; int gr = R0 + (key >> 6); gr = gr > rows - 1 ? rows - 1 : gr;
;         vpre[i] = *(const v4u*)(P + (size_t)(s0 + gr * 64 + (key & 63)) * DIN + C_VC + h * 64 + chunk * 8); }
; __device__ __forceinline__ void mixC_mfma(const bf16* P, const float* rpb  , bf16* MIX, LAS unsigned char* lds, int bid, int G, int tid) {
;     ...
;     const int vb_ = (G % 8 == 0) ? (bid & 7) * (G >> 3) + (bid >> 3) : bid;
;     if (vb_ < NU) c_prefetch(P, vb_, tid, wave, fr, fq, vpre, Qn0, Qn1, Kn);
.LBB0_343:
	s_cmpk_lt_i32 s3, 0x900
	s_cselect_b64 s[0:1], -1, 0
	s_cmpk_gt_i32 s3, 0x8ff
	v_bfe_u32 v110, v208, 4, 2
	s_cbranch_scc1 .LBB0_347
	s_mul_hi_i32 s4, s3, 0x2aaaaaab
	s_lshr_b32 s5, s4, 31
	s_ashr_i32 s4, s4, 5
	s_add_i32 s4, s4, s5
	s_mul_i32 s5, s4, 0xffffff40
	s_add_i32 s5, s5, s3
	s_lshl_b32 s6, s5, 7
	s_cmpk_lt_i32 s5, 0x80
	s_movk_i32 s5, 0xf800
	s_cselect_b32 s5, s5, 0x7ffff000
	s_cselect_b32 s7, 32, 64
	s_and_b32 s11, s5, s6
	s_sub_i32 s5, s6, s11
	s_ashr_i32 s12, s5, 6
	s_max_i32 s5, s12, 4
	s_add_i32 s5, s5, -4
	s_add_i32 s13, s7, -8
	s_min_u32 s5, s5, s13
	v_lshrrev_b32_e32 v1, 3, v208
	v_add_u32_e32 v36, s5, v218
	s_add_i32 s14, s7, -1
	v_and_or_b32 v1, v1, 63, s11
	s_lshl_b32 s4, s4, 6
	v_min_u32_e32 v2, s14, v36
	v_lshlrev_b32_e32 v4, 4, v208
	s_ashr_i32 s5, s4, 31
	v_lshl_add_u32 v2, v2, 6, v1
	s_movk_i32 s9, 0x2c00
	v_mov_b64_e32 v[34:35], s[74:75]
	v_and_b32_e32 v102, 0x70, v4
	v_add_u32_e32 v4, 1, v36
	v_mad_i64_i32 v[2:3], s[6:7], v2, s9, v[34:35]
	s_lshl_b64 s[4:5], s[4:5], 1
	v_min_u32_e32 v4, s14, v4
	v_lshl_add_u64 v[2:3], v[2:3], 0, s[4:5]
	v_mov_b32_e32 v103, 0
	v_lshl_add_u32 v4, v4, 6, v1
	v_add_u32_e32 v10, 2, v36
	v_lshl_add_u64 v[2:3], v[2:3], 0, v[102:103]
	s_movk_i32 s10, 0x2000
	v_mad_i64_i32 v[4:5], s[6:7], v4, s9, v[34:35]
	v_min_u32_e32 v10, s14, v10
	v_add_co_u32_e32 v2, vcc, s10, v2
	v_lshl_add_u64 v[4:5], v[4:5], 0, s[4:5]
	v_lshl_add_u32 v10, v10, 6, v1
	v_add_u32_e32 v12, 3, v36
	v_addc_co_u32_e32 v3, vcc, 0, v3, vcc
	v_lshl_add_u64 v[4:5], v[4:5], 0, v[102:103]
	v_mad_i64_i32 v[10:11], s[6:7], v10, s9, v[34:35]
	v_min_u32_e32 v12, s14, v12
	v_add_co_u32_e32 v6, vcc, s10, v4
	v_lshl_add_u64 v[10:11], v[10:11], 0, s[4:5]
	v_lshl_add_u32 v12, v12, 6, v1
	v_add_u32_e32 v18, 4, v36
	v_addc_co_u32_e32 v7, vcc, 0, v5, vcc
	v_lshl_add_u64 v[10:11], v[10:11], 0, v[102:103]
	v_mad_i64_i32 v[12:13], s[6:7], v12, s9, v[34:35]
	v_min_u32_e32 v18, s14, v18
	v_add_co_u32_e32 v10, vcc, s10, v10
	v_lshl_add_u64 v[12:13], v[12:13], 0, s[4:5]
	v_lshl_add_u32 v18, v18, 6, v1
	v_add_u32_e32 v20, 5, v36
	v_addc_co_u32_e32 v11, vcc, 0, v11, vcc
	v_lshl_add_u64 v[12:13], v[12:13], 0, v[102:103]
	v_mad_i64_i32 v[18:19], s[6:7], v18, s9, v[34:35]
	v_min_u32_e32 v20, s14, v20
	v_add_co_u32_e32 v14, vcc, s10, v12
	v_lshl_add_u64 v[18:19], v[18:19], 0, s[4:5]
	v_lshl_add_u32 v20, v20, 6, v1
	v_add_u32_e32 v26, 6, v36
	v_addc_co_u32_e32 v15, vcc, 0, v13, vcc
	v_lshl_add_u64 v[18:19], v[18:19], 0, v[102:103]
	v_mad_i64_i32 v[20:21], s[6:7], v20, s9, v[34:35]
	v_min_u32_e32 v26, s14, v26
	v_add_co_u32_e32 v18, vcc, s10, v18
	v_lshl_add_u64 v[20:21], v[20:21], 0, s[4:5]
	v_lshl_add_u32 v26, v26, 6, v1
	v_add_u32_e32 v28, 7, v36
	v_addc_co_u32_e32 v19, vcc, 0, v19, vcc
	v_lshl_add_u64 v[20:21], v[20:21], 0, v[102:103]
	v_mad_i64_i32 v[26:27], s[6:7], v26, s9, v[34:35]
	v_min_u32_e32 v28, s14, v28
	v_add_co_u32_e32 v22, vcc, s10, v20
	v_lshl_add_u64 v[26:27], v[26:27], 0, s[4:5]
	v_lshl_add_u32 v28, v28, 6, v1
	v_add_u32_e32 v36, 8, v36
	v_addc_co_u32_e32 v23, vcc, 0, v21, vcc
	v_lshl_add_u64 v[26:27], v[26:27], 0, v[102:103]
	v_mad_i64_i32 v[28:29], s[6:7], v28, s9, v[34:35]
	v_min_u32_e32 v36, s14, v36
	v_add_co_u32_e32 v26, vcc, s10, v26
	v_lshl_add_u64 v[28:29], v[28:29], 0, s[4:5]
	v_lshl_add_u32 v1, v36, 6, v1
	v_addc_co_u32_e32 v27, vcc, 0, v27, vcc
	v_lshl_add_u64 v[28:29], v[28:29], 0, v[102:103]
	v_mad_i64_i32 v[34:35], s[6:7], v1, s9, v[34:35]
	v_add_co_u32_e32 v30, vcc, s10, v28
	v_lshl_add_u64 v[34:35], v[34:35], 0, s[4:5]
	s_nop 0
	v_addc_co_u32_e32 v31, vcc, 0, v29, vcc
	v_lshl_add_u64 v[34:35], v[34:35], 0, v[102:103]
	v_add_co_u32_e32 v34, vcc, 0x2000, v34
	v_mov_b32_e32 v100, v2
	v_mov_b32_e32 v101, v3
	global_load_dwordx4 v[2:5], v[2:3], off
	s_nop 0
	global_load_dwordx4 v[6:9], v[6:7], off
	v_addc_co_u32_e32 v35, vcc, 0, v35, vcc
	global_load_dwordx4 v[10:13], v[10:11], off
	s_nop 0
	global_load_dwordx4 v[14:17], v[14:15], off
	s_nop 0
	global_load_dwordx4 v[18:21], v[18:19], off
	s_nop 0
	global_load_dwordx4 v[22:25], v[22:23], off
	s_nop 0
	global_load_dwordx4 v[26:29], v[26:27], off
	s_nop 0
	global_load_dwordx4 v[30:33], v[30:31], off
	s_bfe_u32 s15, s8, 0x20006
	v_mov_b32_e32 v108, v34
	v_mov_b32_e32 v109, v35
	global_load_dwordx4 v[34:37], v[34:35], off
	s_cmp_lt_i32 s15, 1
	s_mov_b32 s14, s15
	s_cbranch_scc1 .LBB0_350
	s_cmp_eq_u32 s15, 1
	s_cbranch_scc1 .LBB0_348
	s_cmp_eq_u32 s15, 2
	s_cselect_b32 s14, 24, 32
	s_cbranch_execz .LBB0_349
	s_branch .LBB0_350

; __device__ __forceinline__ void c_prefetch(const bf16* P, int un, int tid, int wave, int fr, int fq, v4u (&vpre)[9], bf16x8& Q0, bf16x8& Q1, bf16x8 (&K)[8][2]) {
;     ...
;     const int r = rf + (wave >> 2), j = wave & 3;
;     int rs = r - 4; rs = rs < 0 ? 0 : rs; rs = rs > rows - 8 ? rows - 8 : rs;
;     const int kcol0 = j == 0 ? 0 : (j == 1 ? 8 : (j == 2 ? 24 : 32));
;     { const bf16* qp = P + (size_t)(s0 + r * 64 + 16 * j + fr) * DIN + C_QC + h * 64 + fq * 8; Q0 = *(const bf16x8*)qp; Q1 = *(const bf16x8*)(qp + 32); }
; #pragma unroll
;     for (int kt = 0; kt < 8; ++kt) { const bf16* kp = P + (size_t)(s0 + (rs + (kt >> 1)) * 64 + kcol0 + 16 * (kt & 1) + fr) * DIN + C_KC + h * 64 + fq * 8;
;         K[kt][0] = *(const bf16x8*)kp; K[kt][1] = *(const bf16x8*)(kp + 32); }
.LBB0_350:
	s_lshr_b32 s6, s8, 8
	s_add_i32 s12, s12, s6
	s_max_i32 s6, s12, 4
	s_add_i32 s6, s6, -4
	s_min_u32 s13, s6, s13
	s_lshl_b32 s6, s12, 6
	s_add_i32 s6, s6, s11
	s_lshl_b32 s7, s15, 4
	s_or_b32 s6, s6, s7
	v_or_b32_e32 v1, s6, v207
	v_mov_b64_e32 v[104:105], s[74:75]
	v_mad_i64_i32 v[38:39], s[6:7], v1, s9, v[104:105]
	v_lshl_add_u64 v[38:39], v[38:39], 0, s[4:5]
	v_lshlrev_b32_e32 v102, 4, v110
	v_or_b32_e32 v1, s11, v207
	v_lshl_add_u64 v[38:39], v[38:39], 0, v[102:103]
	s_mov_b64 s[6:7], 0x1a00
	v_add_u32_e32 v1, s14, v1
	s_lshl_b32 s11, s13, 6
	v_lshl_add_u64 v[42:43], v[38:39], 0, s[6:7]
	s_movk_i32 s6, 0x1000
	v_add_u32_e32 v46, s11, v1
	v_add_co_u32_e32 v38, vcc, s6, v38
	v_mad_i64_i32 v[46:47], s[6:7], v46, s9, v[104:105]
	v_add_u32_e32 v106, 16, v1
	v_lshl_add_u64 v[46:47], v[46:47], 0, s[4:5]
	v_add_u32_e32 v54, s11, v106
	v_addc_co_u32_e32 v39, vcc, 0, v39, vcc
	v_lshl_add_u64 v[46:47], v[46:47], 0, v[102:103]
	s_mov_b64 s[6:7], 0x2000
	v_mad_i64_i32 v[54:55], s[12:13], v54, s9, v[104:105]
	s_add_i32 s14, s11, 64
	v_lshl_add_u64 v[50:51], v[46:47], 0, s[6:7]
	v_add_co_u32_e32 v46, vcc, s10, v46
	v_lshl_add_u64 v[54:55], v[54:55], 0, s[4:5]
	v_add_u32_e32 v62, s14, v1
	v_addc_co_u32_e32 v47, vcc, 0, v47, vcc
	v_lshl_add_u64 v[54:55], v[54:55], 0, v[102:103]
	v_mad_i64_i32 v[62:63], s[12:13], v62, s9, v[104:105]
	v_lshl_add_u64 v[58:59], v[54:55], 0, s[6:7]
	v_add_co_u32_e32 v54, vcc, s10, v54
	v_lshl_add_u64 v[62:63], v[62:63], 0, s[4:5]
	v_add_u32_e32 v70, s14, v106
	v_addc_co_u32_e32 v55, vcc, 0, v55, vcc
	v_lshl_add_u64 v[62:63], v[62:63], 0, v[102:103]
	v_mad_i64_i32 v[70:71], s[12:13], v70, s9, v[104:105]
	s_add_i32 s14, s11, 0x80
	v_lshl_add_u64 v[66:67], v[62:63], 0, s[6:7]
	v_add_co_u32_e32 v62, vcc, s10, v62
	v_lshl_add_u64 v[70:71], v[70:71], 0, s[4:5]
	v_add_u32_e32 v78, s14, v1
	v_addc_co_u32_e32 v63, vcc, 0, v63, vcc
	v_lshl_add_u64 v[70:71], v[70:71], 0, v[102:103]
	v_mad_i64_i32 v[78:79], s[12:13], v78, s9, v[104:105]
	v_lshl_add_u64 v[74:75], v[70:71], 0, s[6:7]
	v_add_co_u32_e32 v70, vcc, s10, v70
	v_lshl_add_u64 v[78:79], v[78:79], 0, s[4:5]
	v_add_u32_e32 v86, s14, v106
	v_addc_co_u32_e32 v71, vcc, 0, v71, vcc
	v_lshl_add_u64 v[78:79], v[78:79], 0, v[102:103]
	v_mad_i64_i32 v[86:87], s[12:13], v86, s9, v[104:105]
	s_addk_i32 s11, 0xc0
	v_lshl_add_u64 v[80:81], v[78:79], 0, s[6:7]
	v_add_co_u32_e32 v78, vcc, s10, v78
	v_lshl_add_u64 v[86:87], v[86:87], 0, s[4:5]
	v_add_u32_e32 v1, s11, v1
	v_addc_co_u32_e32 v79, vcc, 0, v79, vcc
	v_lshl_add_u64 v[86:87], v[86:87], 0, v[102:103]
	v_mad_i64_i32 v[94:95], s[12:13], v1, s9, v[104:105]
	v_lshl_add_u64 v[90:91], v[86:87], 0, s[6:7]
	v_add_co_u32_e32 v86, vcc, s10, v86
	v_lshl_add_u64 v[94:95], v[94:95], 0, s[4:5]
	s_nop 0
	v_addc_co_u32_e32 v87, vcc, 0, v87, vcc
	v_lshl_add_u64 v[94:95], v[94:95], 0, v[102:103]
	v_add_u32_e32 v1, s11, v106
	v_lshl_add_u64 v[98:99], v[94:95], 0, s[6:7]
	v_add_co_u32_e32 v94, vcc, s10, v94
	v_mad_i64_i32 v[104:105], s[10:11], v1, s9, v[104:105]
	v_lshl_add_u64 v[104:105], v[104:105], 0, s[4:5]
	v_addc_co_u32_e32 v95, vcc, 0, v95, vcc
	v_lshl_add_u64 v[102:103], v[104:105], 0, v[102:103]
	v_lshl_add_u64 v[106:107], v[102:103], 0, s[6:7]
	v_add_co_u32_e32 v102, vcc, 0x2000, v102
	global_load_dwordx4 v[38:41], v[38:39], off offset:2560
	s_nop 0
	global_load_dwordx4 v[42:45], v[42:43], off offset:64
	v_addc_co_u32_e32 v103, vcc, 0, v103, vcc
	s_nop 0
	s_nop 0
	s_nop 0
	s_nop 0
	s_nop 0
	s_nop 0
	s_nop 0
	s_nop 0
	s_nop 0
	s_nop 0
	s_nop 0
	s_nop 0
	s_nop 0
	s_nop 0
	s_nop 0
	s_nop 0
	s_nop 0
	s_nop 0
	s_nop 0
	s_nop 0
	s_nop 0
	s_nop 0
	s_nop 0
	s_nop 0
	s_nop 0
	s_nop 0
	s_nop 0
	s_nop 0
	s_nop 0
	s_nop 0
	s_nop 0
	s_andn2_b64 vcc, exec, s[0:1]
	s_cbranch_vccnz .LBB0_493

; #define LAS __attribute__((address_space(3)))
; __device__ __forceinline__ void seq_of(int row, int& s0, int& T) { if (row < MP) { s0 = row & ~2047; T = 2048; } else { s0 = MP + ((row - MP) & ~4095); T = 4096; } }
; __device__ __forceinline__ void mixC_mfma(const bf16* P, const float* rpb  , bf16* MIX, LAS unsigned char* lds, int bid, int G, int tid) {
;     ...
;     for (int un = vb_; un < NU; un += G) {
;         const int h = un / (M / 128), blk = un - h * (M / 128), row0 = blk * 128; int s0, T; seq_of(row0, s0, T);
;         const int rows = T >> 6, rf = (row0 - s0) >> 6;
;         int R0 = rf - 4; R0 = R0 < 0 ? 0 : R0; R0 = R0 > rows - 8 ? rows - 8 : R0;
;         __syncthreads();
; #pragma unroll
;         for (int i = 0; i < 9; ++i) { const int e = tid + i * NTHREADS; *(LAS v4u*)(Vs + (e >> 3) * VROW + (e & 7) * 16) = vpre[i]; }
;         __syncthreads();
.LBB0_353:
	s_mul_hi_i32 s0, s3, 0x2aaaaaab
	s_lshr_b32 s1, s0, 31
	s_ashr_i32 s4, s0, 5
	s_add_i32 s4, s4, s1
	s_mul_i32 s0, s4, 0xffffff40
	s_mul_i32 s1, s4, 0xffffa000
	s_add_i32 s0, s3, s0
	s_add_i32 s1, s34, s1
	s_cmpk_lt_i32 s0, 0x80
	s_cselect_b32 s0, s78, 0x7ffff000
	s_cselect_b32 s5, 24, 56
	s_and_b32 s89, s0, s1
	s_mul_i32 s0, s4, 0x6000
	s_add_i32 s0, s89, s0
	s_sub_i32 s0, s34, s0
	s_ashr_i32 s90, s0, 6
	s_max_i32 s0, s90, 4
	s_add_i32 s0, s0, -4
	s_min_u32 s91, s0, s5
	s_cmp_lt_i32 s13, 1
	s_mov_b32 s35, s13
	s_waitcnt lgkmcnt(0)
	s_barrier
	s_waitcnt vmcnt(10)
	ds_write_b128 v223, v[2:5]
	s_waitcnt vmcnt(9)
	ds_write_b128 v226, v[6:9]
	s_waitcnt vmcnt(8)
	ds_write_b128 v223, v[10:13] offset:20480
	s_waitcnt vmcnt(7)
	ds_write_b128 v227, v[14:17]
	s_waitcnt vmcnt(6)
	ds_write_b128 v223, v[18:21] offset:40960
	s_waitcnt vmcnt(5)
	ds_write_b128 v228, v[22:25]
	s_waitcnt vmcnt(4)
	ds_write_b128 v223, v[26:29] offset:61440
	s_waitcnt vmcnt(3)
	ds_write_b128 v229, v[30:33]
	s_waitcnt vmcnt(2)
	ds_write_b128 v224, v[34:37]
	s_waitcnt lgkmcnt(0)
	s_barrier
	v_mov_b32_e32 v252, 0xb0000
	v_mov_b32_e32 v253, 0
	v_lshl_add_u64 v[6:7], v[100:101], 0, v[252:253]
	v_lshl_add_u64 v[10:11], v[6:7], 0, v[252:253]
	v_lshl_add_u64 v[14:15], v[10:11], 0, v[252:253]
	v_lshl_add_u64 v[18:19], v[14:15], 0, v[252:253]
	v_lshl_add_u64 v[22:23], v[18:19], 0, v[252:253]
	v_lshl_add_u64 v[26:27], v[22:23], 0, v[252:253]
	v_lshl_add_u64 v[30:31], v[26:27], 0, v[252:253]
	v_mov_b32_e32 v34, v108
	v_mov_b32_e32 v35, v109
	v_mov_b32_e32 v2, v100
	v_mov_b32_e32 v3, v101
	global_load_dwordx4 v[2:5], v[2:3], off offset:1536
	global_load_dwordx4 v[6:9], v[6:7], off offset:1536
	global_load_dwordx4 v[10:13], v[10:11], off offset:1536
	global_load_dwordx4 v[14:17], v[14:15], off offset:1536
	global_load_dwordx4 v[18:21], v[18:19], off offset:1536
	global_load_dwordx4 v[22:25], v[22:23], off offset:1536
	global_load_dwordx4 v[26:29], v[26:27], off offset:1536
	global_load_dwordx4 v[30:33], v[30:31], off offset:1536
	global_load_dwordx4 v[34:37], v[34:35], off offset:1536
	s_cbranch_scc1 .LBB0_358
	s_cmp_eq_u32 s13, 1
	s_mov_b64 s[0:1], -1
	s_cbranch_scc1 .LBB0_356
	s_mov_b64 s[0:1], 0

; __device__ __forceinline__ void mixC_mfma(const bf16* P, const float* rpb  , bf16* MIX, LAS unsigned char* lds, int bid, int G, int tid) {
;     ...
;         const int r = rf + (wave >> 2), j = wave & 3;
;         int rs = r - 4; rs = rs < 0 ? 0 : rs; rs = rs > rows - 8 ? rows - 8 : rs;
;         const int kcol0 = j == 0 ? 0 : (j == 1 ? 8 : (j == 2 ? 24 : 32));
;         const int c = 16 * j + fr; int cs = c - 8; cs = cs < 0 ? 0 : cs; cs = cs > 48 ? 48 : cs;
;         const size_t qrow = (size_t)(s0 + r * 64 + c);
;         f32x4 S[16];
;         bf16x8 Kl[8][2];
; #pragma unroll
;         for (int kt = 8; kt < 16; ++kt) { const bf16* kp = P + (size_t)(s0 + (rs + (kt >> 1)) * 64 + kcol0 + 16 * (kt & 1) + fr) * DIN + C_KC + h * 64 + fq * 8;
;             Kl[kt - 8][0] = *(const bf16x8*)kp; Kl[kt - 8][1] = *(const bf16x8*)(kp + 32); }
; #pragma unroll
;         for (int kt = 0; kt < 8; ++kt) { f32x4 z = {0.f, 0.f, 0.f, 0.f};
;             z = __builtin_amdgcn_mfma_f32_16x16x32_bf16(Kn[kt][0], Qn0, z, 0, 0, 0);
;             S[kt] = __builtin_amdgcn_mfma_f32_16x16x32_bf16(Kn[kt][1], Qn1, z, 0, 0, 0); }
.LBB0_358:
	s_add_i32 s90, s90, s12
	s_max_i32 s0, s90, 4
	s_add_i32 s0, s0, -4
	s_min_u32 s92, s0, s5
	v_mov_b32_e32 v253, s91
	v_sub_u32_e32 v253, s92, v253
	v_lshl_add_u32 v253, v253, 6, s35
	v_mul_u32_u24_e32 v253, 0xa0, v253
	v_and_b32_e32 v255, 15, v208
	v_mul_u32_u24_e32 v255, 0xa0, v255
	v_bfe_u32 v254, v208, 4, 2
	v_lshl_add_u32 v255, v254, 4, v255
	v_add_u32_e32 v255, v253, v255
	v_add_u32_e32 v254, 0xa000, v255
	ds_read_b128 v[46:49], v255
	ds_read_b128 v[50:53], v255 offset:64
	ds_read_b128 v[54:57], v255 offset:2560
	ds_read_b128 v[58:61], v255 offset:2624
	ds_read_b128 v[62:65], v255 offset:10240
	ds_read_b128 v[66:69], v255 offset:10304
	ds_read_b128 v[70:73], v255 offset:12800
	ds_read_b128 v[74:77], v255 offset:12864
	ds_read_b128 v[82:85], v255 offset:20480
	ds_read_b128 v[78:81], v255 offset:20544
	ds_read_b128 v[86:89], v255 offset:23040
	ds_read_b128 v[90:93], v255 offset:23104
	ds_read_b128 v[94:97], v255 offset:30720
	ds_read_b128 v[98:101], v255 offset:30784
	ds_read_b128 v[102:105], v255 offset:33280
	ds_read_b128 v[106:109], v255 offset:33344
	s_waitcnt lgkmcnt(0)
	v_or_b32_e32 v110, s89, v207
	s_lshl_b32 s5, s92, 6
	v_add_u32_e32 v162, s35, v110
	s_add_i32 s6, s5, 0x100
	s_lshl_b32 s80, s4, 6
	v_add_u32_e32 v110, s6, v162
	v_mov_b64_e32 v[170:171], s[74:75]
	s_ashr_i32 s81, s80, 31
	v_mad_i64_i32 v[110:111], s[0:1], v110, s79, v[170:171]
	s_lshl_b64 s[0:1], s[80:81], 1
	v_add_u32_e32 v172, 16, v162
	v_lshl_add_u64 v[110:111], v[110:111], 0, s[0:1]
	v_add_u32_e32 v118, s6, v172
	v_lshl_add_u64 v[110:111], v[110:111], 0, v[210:211]
	v_mad_i64_i32 v[118:119], s[6:7], v118, s79, v[170:171]
	s_add_i32 s8, s5, 0x140
	s_waitcnt vmcnt(9)
	v_mfma_f32_16x16x32_bf16 v[142:145], v[46:49], v[38:41], 0
	v_lshl_add_u64 v[114:115], v[110:111], 0, s[22:23]
	v_add_co_u32_e32 v110, vcc, s88, v110
	v_lshl_add_u64 v[118:119], v[118:119], 0, s[0:1]
	v_add_u32_e32 v126, s8, v162
	v_addc_co_u32_e32 v111, vcc, 0, v111, vcc
	v_lshl_add_u64 v[118:119], v[118:119], 0, v[210:211]
	v_mad_i64_i32 v[126:127], s[6:7], v126, s79, v[170:171]
	v_lshl_add_u64 v[122:123], v[118:119], 0, s[22:23]
	v_add_co_u32_e32 v118, vcc, s88, v118
	v_lshl_add_u64 v[126:127], v[126:127], 0, s[0:1]
	v_add_u32_e32 v134, s8, v172
	s_add_i32 s8, s5, 0x180
	v_addc_co_u32_e32 v119, vcc, 0, v119, vcc
	v_lshl_add_u64 v[126:127], v[126:127], 0, v[210:211]
	v_mad_i64_i32 v[134:135], s[6:7], v134, s79, v[170:171]
	s_waitcnt vmcnt(14)
	v_mfma_f32_16x16x32_bf16 v[202:205], v[50:53], v[42:45], v[142:145]
	v_lshl_add_u64 v[130:131], v[126:127], 0, s[22:23]
	v_add_co_u32_e32 v126, vcc, s88, v126
	s_nop 0
	v_add_u32_e32 v142, s8, v162
	v_lshl_add_u64 v[134:135], v[134:135], 0, s[0:1]
	v_mad_i64_i32 v[146:147], s[6:7], v142, s79, v[170:171]
	s_waitcnt vmcnt(13)
	v_mfma_f32_16x16x32_bf16 v[142:145], v[54:57], v[38:41], 0
	v_addc_co_u32_e32 v127, vcc, 0, v127, vcc
	v_lshl_add_u64 v[134:135], v[134:135], 0, v[210:211]
	v_lshl_add_u64 v[136:137], v[134:135], 0, s[22:23]
	v_add_co_u32_e32 v134, vcc, s88, v134
	v_lshl_add_u64 v[146:147], v[146:147], 0, s[0:1]
	s_nop 0
	v_addc_co_u32_e32 v135, vcc, 0, v135, vcc
	v_lshl_add_u64 v[146:147], v[146:147], 0, v[210:211]
	s_waitcnt vmcnt(12)
	v_mfma_f32_16x16x32_bf16 v[198:201], v[58:61], v[42:45], v[142:145]
	v_lshl_add_u64 v[150:151], v[146:147], 0, s[22:23]
	ds_read_b128 v[110:113], v254
	s_nop 0
	ds_read_b128 v[114:117], v254 offset:64
	v_add_co_u32_e32 v142, vcc, s88, v146
	ds_read_b128 v[118:121], v254 offset:2560
	s_nop 0
	ds_read_b128 v[122:125], v254 offset:2624
	v_addc_co_u32_e32 v143, vcc, 0, v147, vcc
	ds_read_b128 v[126:129], v254 offset:10240
	s_nop 0
	ds_read_b128 v[130:133], v254 offset:10304
	s_nop 0
	ds_read_b128 v[138:141], v254 offset:12800
	s_nop 0
	ds_read_b128 v[134:137], v254 offset:12864
	s_nop 0
	ds_read_b128 v[146:149], v254 offset:20480
	s_nop 0
	ds_read_b128 v[142:145], v254 offset:20544
	s_waitcnt vmcnt(21)
; #define LAS __attribute__((address_space(3)))
; __device__ __forceinline__ void mixC_mfma(const bf16* P, const float* rpb  , bf16* MIX, LAS unsigned char* lds, int bid, int G, int tid) {
;     ...
; #pragma unroll
;         for (int kt = 8; kt < 16; ++kt) { const bf16* kp = P + (size_t)(s0 + (rs + (kt >> 1)) * 64 + kcol0 + 16 * (kt & 1) + fr) * DIN + C_KC + h * 64 + fq * 8;
;             Kl[kt - 8][0] = *(const bf16x8*)kp; Kl[kt - 8][1] = *(const bf16x8*)(kp + 32); }
; #pragma unroll
;         for (int kt = 0; kt < 8; ++kt) { f32x4 z = {0.f, 0.f, 0.f, 0.f};
;             z = __builtin_amdgcn_mfma_f32_16x16x32_bf16(Kn[kt][0], Qn0, z, 0, 0, 0);
;             S[kt] = __builtin_amdgcn_mfma_f32_16x16x32_bf16(Kn[kt][1], Qn1, z, 0, 0, 0); }
;         const int d0 = kcol0 + 4 * fq - cs;
;         const LAS float* rpl = rp + h * 512 + (rs - r + 7) * 31 + (kcol0 + 4 * fq - c + 15);
;         float m1 = -1e30f;
; #pragma unroll
;         for (int kt = 0; kt < 8; ++kt)
; #pragma unroll
;             for (int t = 0; t < 4; ++t) {
;                 const bool ok = (unsigned)(d0 + 16 * (kt & 1) + t) < 16u;
;                 const float sv = ok ? S[kt][t] * (0.125f * L2E) + rpl[(kt >> 1) * 31 + 16 * (kt & 1) + t] : -1e30f;
;                 S[kt][t] = sv; m1 = fmaxf(m1, sv);
	v_mfma_f32_16x16x32_bf16 v[150:153], v[62:65], v[38:41], 0
	v_add_u32_e32 v154, s8, v172
	v_mad_i64_i32 v[154:155], s[6:7], v154, s79, v[170:171]
	s_waitcnt vmcnt(20)
	v_mfma_f32_16x16x32_bf16 v[194:197], v[66:69], v[42:45], v[150:153]
	s_addk_i32 s5, 0x1c0
	v_add_u32_e32 v162, s5, v162
	v_mad_i64_i32 v[162:163], s[6:7], v162, s79, v[170:171]
	s_nop 0
	v_lshl_add_u64 v[150:151], v[154:155], 0, s[0:1]
	v_lshl_add_u64 v[154:155], v[150:151], 0, v[210:211]
	s_waitcnt vmcnt(19)
	v_mfma_f32_16x16x32_bf16 v[150:153], v[70:73], v[38:41], 0
	v_lshl_add_u64 v[158:159], v[154:155], 0, s[22:23]
	v_add_co_u32_e32 v154, vcc, s88, v154
	s_waitcnt vmcnt(15)
	v_mfma_f32_16x16x32_bf16 v[166:169], v[86:89], v[38:41], 0
	v_addc_co_u32_e32 v155, vcc, 0, v155, vcc
	v_add_u32_e32 v217, s35, v212
	v_mfma_f32_16x16x32_bf16 v[190:193], v[74:77], v[42:45], v[150:153]
	ds_read_b128 v[154:157], v254 offset:23040
	s_nop 1
	ds_read_b128 v[150:153], v254 offset:23104
	v_sub_u32_e32 v215, v217, v209
	v_sub_u32_e32 v217, v217, v1
	v_mfma_f32_16x16x32_bf16 v[158:161], v[82:85], v[38:41], 0
	s_waitcnt vmcnt(16)
	v_mfma_f32_16x16x32_bf16 v[182:185], v[90:93], v[42:45], v[166:169]
	s_nop 2
	v_add_u32_e32 v166, s5, v172
	v_mfma_f32_16x16x32_bf16 v[186:189], v[78:81], v[42:45], v[158:161]
	v_mad_i64_i32 v[170:171], s[6:7], v166, s79, v[170:171]
	v_lshl_add_u64 v[170:171], v[170:171], 0, s[0:1]
	s_nop 0
	v_lshl_add_u64 v[158:159], v[162:163], 0, s[0:1]
	s_waitcnt vmcnt(15)
	v_mfma_f32_16x16x32_bf16 v[166:169], v[94:97], v[38:41], 0
	v_lshl_add_u64 v[158:159], v[158:159], 0, v[210:211]
	v_lshl_add_u64 v[160:161], v[158:159], 0, s[22:23]
	v_add_co_u32_e32 v158, vcc, s88, v158
	v_lshl_add_u64 v[170:171], v[170:171], 0, v[210:211]
	s_nop 0
	v_addc_co_u32_e32 v159, vcc, 0, v159, vcc
	s_waitcnt vmcnt(14)
	v_mfma_f32_16x16x32_bf16 v[178:181], v[98:101], v[42:45], v[166:169]
	ds_read_b128 v[162:165], v254 offset:30720
	s_nop 0
	ds_read_b128 v[158:161], v254 offset:30784
	v_add_co_u32_e32 v166, vcc, s88, v170
	v_lshl_add_u64 v[230:231], v[170:171], 0, s[22:23]
	s_nop 0
	v_addc_co_u32_e32 v167, vcc, 0, v171, vcc
	ds_read_b128 v[170:173], v254 offset:33280
	s_nop 0
	ds_read_b128 v[166:169], v254 offset:33344
	s_waitcnt vmcnt(17)
	v_mfma_f32_16x16x32_bf16 v[174:177], v[102:105], v[38:41], 0
	s_lshl_b32 s0, s4, 11
	s_sub_i32 s1, s92, s90
	s_add_i32 s0, s0, 0
	s_waitcnt vmcnt(16)
	v_mfma_f32_16x16x32_bf16 v[174:177], v[106:109], v[42:45], v[174:177]
	s_mulk_i32 s1, 0x7c
	s_add_i32 s0, s0, s1
	v_add_u32_e32 v230, 8, v215
	s_add_i32 s0, s0, 0x16800
	v_lshl_add_u32 v231, v217, 2, s0
	s_waitcnt lgkmcnt(0)
	ds_read_b32 v46, v231 offset:928
	ds_read_b32 v47, v231 offset:932
	ds_read_b32 v48, v231 offset:936
	ds_read_b32 v49, v231 offset:940
	ds_read_b32 v50, v231 offset:992
	ds_read_b32 v51, v231 offset:996
	ds_read_b32 v52, v231 offset:1000
	ds_read_b32 v53, v231 offset:1004
	ds_read_b32 v54, v231 offset:1052
	ds_read_b32 v55, v231 offset:1056
	ds_read_b32 v56, v231 offset:1060
	ds_read_b32 v57, v231 offset:1064
	ds_read_b32 v58, v231 offset:1116
	ds_read_b32 v59, v231 offset:1120
	ds_read_b32 v60, v231 offset:1124
	ds_read_b32 v61, v231 offset:1128
	v_cmp_gt_u32_e64 s[0:1], 16, v230
	v_mov_b32_e32 v217, 0xf149f2ca
	v_mov_b32_e32 v230, 0xf149f2ca
	s_and_saveexec_b64 s[4:5], s[0:1]
	s_cbranch_execz .LBB0_360
	s_waitcnt lgkmcnt(0)
	v_fmamk_f32 v230, v202, 0x3e38aa3b, v46

; #define LAS __attribute__((address_space(3)))
; __device__ __forceinline__ void mixC_mfma(const bf16* P, const float* rpb  , bf16* MIX, LAS unsigned char* lds, int bid, int G, int tid) {
;     ...
; #pragma unroll
;         for (int i = 0; i < 9; ++i) { const int e = tid + i * NTHREADS; *(LAS v4u*)(Vs + (e >> 3) * VROW + (e & 7) * 16) = vpre[i]; }
;         __syncthreads();
;     ...
;         for (int kt = 8; kt < 16; ++kt) { f32x4 z = {0.f, 0.f, 0.f, 0.f};
;             z = __builtin_amdgcn_mfma_f32_16x16x32_bf16(Kl[kt - 8][0], Qn0, z, 0, 0, 0);
;             S[kt] = __builtin_amdgcn_mfma_f32_16x16x32_bf16(Kl[kt - 8][1], Qn1, z, 0, 0, 0); }
;         asm volatile("" ::: "memory");
.LBB0_422:
	s_or_b64 exec, exec, s[82:83]
	s_waitcnt lgkmcnt(0)
	v_mfma_f32_16x16x32_bf16 v[110:113], v[110:113], v[38:41], 0
	s_mov_b32 s24, 0xf149f2ca
	s_add_i32 s3, s3, s68
	s_nop 0
	v_mfma_f32_16x16x32_bf16 v[178:181], v[114:117], v[42:45], v[110:113]
	v_max3_f32 v114, v230, s24, v217
	s_cmpk_gt_i32 s3, 0x8ff
	s_cselect_b64 s[82:83], -1, 0
	s_nop 0
	v_mfma_f32_16x16x32_bf16 v[110:113], v[118:121], v[38:41], 0
	s_and_b64 vcc, exec, s[82:83]
	s_nop 0
	v_mfma_f32_16x16x32_bf16 v[174:177], v[122:125], v[42:45], v[110:113]
	s_nop 0
	v_mfma_f32_16x16x32_bf16 v[110:113], v[126:129], v[38:41], 0
	s_nop 0
	v_mfma_f32_16x16x32_bf16 v[130:133], v[130:133], v[42:45], v[110:113]
	s_nop 0
	v_mfma_f32_16x16x32_bf16 v[110:113], v[138:141], v[38:41], 0
	s_nop 0
	v_mfma_f32_16x16x32_bf16 v[126:129], v[134:137], v[42:45], v[110:113]
	s_nop 5
	v_max3_f32 v110, v114, v203, v202
	v_max3_f32 v110, v110, v205, v204
	v_max3_f32 v114, v110, v199, v198
	s_nop 0
	v_mfma_f32_16x16x32_bf16 v[110:113], v[146:149], v[38:41], 0
	v_max3_f32 v114, v114, v201, v200
	v_max3_f32 v114, v114, v195, v194
	v_max3_f32 v114, v114, v197, v196
	s_nop 0
	v_mfma_f32_16x16x32_bf16 v[122:125], v[142:145], v[42:45], v[110:113]
	s_nop 2
	v_max3_f32 v110, v114, v191, v190
	v_max3_f32 v110, v110, v193, v192
	v_max3_f32 v114, v110, v187, v186
	s_nop 0
	v_mfma_f32_16x16x32_bf16 v[110:113], v[154:157], v[38:41], 0
	v_max3_f32 v114, v114, v189, v188
	v_max3_f32 v114, v114, v183, v182
	v_max3_f32 v114, v114, v185, v184
	s_nop 0
	v_mfma_f32_16x16x32_bf16 v[118:121], v[150:153], v[42:45], v[110:113]
	s_nop 2
	v_max3_f32 v110, v114, v233, v232
	v_max3_f32 v110, v110, v235, v234
	v_max3_f32 v114, v110, v237, v236
	ds_bpermute_b32 v115, v219, v114
	s_nop 0
	v_mfma_f32_16x16x32_bf16 v[110:113], v[162:165], v[38:41], 0
	s_waitcnt lgkmcnt(0)
	v_max_f32_e32 v115, v115, v115
	v_max_f32_e32 v134, v114, v115
	s_nop 0
	v_mfma_f32_16x16x32_bf16 v[114:117], v[158:161], v[42:45], v[110:113]
	ds_bpermute_b32 v135, v220, v134
	s_nop 0
	v_mfma_f32_16x16x32_bf16 v[110:113], v[170:173], v[38:41], 0
	s_nop 0
	v_mfma_f32_16x16x32_bf16 v[110:113], v[166:169], v[42:45], v[110:113]
	s_waitcnt vmcnt(0)
	s_waitcnt lgkmcnt(0)
	s_barrier
	ds_write_b128 v223, v[2:5]
	ds_write_b128 v226, v[6:9]
	ds_write_b128 v223, v[10:13] offset:20480
	ds_write_b128 v227, v[14:17]
	ds_write_b128 v223, v[18:21] offset:40960
	ds_write_b128 v228, v[22:25]
	ds_write_b128 v223, v[26:29] offset:61440
	ds_write_b128 v229, v[30:33]
	ds_write_b128 v224, v[34:37]
	s_waitcnt lgkmcnt(0)
	s_barrier
	ds_read_b32 v239, v231 offset:1424
	ds_read_b32 v240, v231 offset:1428
	ds_read_b32 v241, v231 offset:1432
	ds_read_b32 v242, v231 offset:1436
	ds_read_b32 v243, v231 offset:1488
	ds_read_b32 v244, v231 offset:1492
	ds_read_b32 v245, v231 offset:1496
	ds_read_b32 v246, v231 offset:1500
	ds_read_b32 v247, v231 offset:1548
	ds_read_b32 v248, v231 offset:1552
	ds_read_b32 v249, v231 offset:1556
	ds_read_b32 v250, v231 offset:1560
	ds_read_b32 v251, v231 offset:1612
	ds_read_b32 v252, v231 offset:1616
	ds_read_b32 v253, v231 offset:1620
	ds_read_b32 v254, v231 offset:1624
	s_cbranch_vccz .LBB0_486
	v_mov_b32_e32 v138, 0xf149f2ca
	v_mov_b32_e32 v139, 0xf149f2ca
	s_and_saveexec_b64 s[84:85], s[0:1]
	s_cbranch_execnz .LBB0_492

; __device__ __forceinline__ void seq_of(int row, int& s0, int& T) { if (row < MP) { s0 = row & ~2047; T = 2048; } else { s0 = MP + ((row - MP) & ~4095); T = 4096; } }
; __device__ __forceinline__ void c_prefetch(const bf16* P, int un, int tid, int wave, int fr, int fq, v4u (&vpre)[9], bf16x8& Q0, bf16x8& Q1, bf16x8 (&K)[8][2]) {
;     const int h = un / (M / 128), blk = un - h * (M / 128), row0 = blk * 128; int s0, T; seq_of(row0, s0, T);
;     const int rows = T >> 6, rf = (row0 - s0) >> 6;
;     int R0 = rf - 4; R0 = R0 < 0 ? 0 : R0; R0 = R0 > rows - 8 ? rows - 8 : R0;
; #pragma unroll
;     for (int i = 0; i < 9; ++i) { const int e = tid + i * NTHREADS, key = e >> 3, chunk = e & 7; int gr = R0 + (key >> 6); gr = gr > rows - 1 ? rows - 1 : gr;
;         vpre[i] = *(const v4u*)(P + (size_t)(s0 + gr * 64 + (key & 63)) * DIN + C_VC + h * 64 + chunk * 8); }
.LBB0_486:
	s_mul_hi_i32 s24, s3, 0x2aaaaaab
	s_lshr_b32 s25, s24, 31
	s_ashr_i32 s24, s24, 5
	s_add_i32 s24, s24, s25
	s_mul_i32 s25, s24, 0xffffff40
	s_mul_i32 s26, s24, 0xffffa000
	s_add_i32 s27, s33, s34
	s_add_i32 s25, s3, s25
	s_add_i32 s26, s27, s26
	s_cmpk_lt_i32 s25, 0x80
	s_cselect_b32 s25, s78, 0x7ffff000
	s_cselect_b32 s36, 32, 64
	s_and_b32 s26, s25, s26
	s_mul_i32 s25, s24, 0x6000
	s_add_i32 s25, s26, s25
	s_sub_i32 s25, s27, s25
	s_ashr_i32 s27, s25, 6
	s_max_i32 s25, s27, 4
	s_add_i32 s25, s25, -4
	s_add_i32 s93, s36, -8
	s_min_u32 s25, s25, s93
	v_add_u32_e32 v36, s25, v218
	s_add_i32 s36, s36, -1
	v_or_b32_e32 v37, s26, v221
	v_min_u32_e32 v2, s36, v36
	s_lshl_b32 s24, s24, 6
	v_lshl_add_u32 v2, v2, 6, v37
	v_mov_b64_e32 v[34:35], s[74:75]
	s_ashr_i32 s25, s24, 31
	v_mad_i64_i32 v[2:3], s[84:85], v2, s79, v[34:35]
	v_add_u32_e32 v4, 1, v36
	s_lshl_b64 s[84:85], s[24:25], 1
	v_min_u32_e32 v4, s36, v4
	v_lshl_add_u64 v[2:3], v[2:3], 0, s[84:85]
	v_mov_b32_e32 v215, v211
	v_lshl_add_u32 v4, v4, 6, v37
	v_add_u32_e32 v10, 2, v36
	v_lshl_add_u64 v[2:3], v[2:3], 0, v[214:215]
	v_mad_i64_i32 v[4:5], s[24:25], v4, s79, v[34:35]
	v_min_u32_e32 v10, s36, v10
	v_add_co_u32_e32 v2, vcc, s88, v2
	v_lshl_add_u64 v[4:5], v[4:5], 0, s[84:85]
	v_lshl_add_u32 v10, v10, 6, v37
	v_add_u32_e32 v12, 3, v36
	v_addc_co_u32_e32 v3, vcc, 0, v3, vcc
	v_lshl_add_u64 v[4:5], v[4:5], 0, v[214:215]
	v_mad_i64_i32 v[10:11], s[24:25], v10, s79, v[34:35]
	v_min_u32_e32 v12, s36, v12
	v_add_co_u32_e32 v6, vcc, s88, v4
	v_lshl_add_u64 v[10:11], v[10:11], 0, s[84:85]
	v_lshl_add_u32 v12, v12, 6, v37
	v_add_u32_e32 v18, 4, v36
	v_addc_co_u32_e32 v7, vcc, 0, v5, vcc
	v_lshl_add_u64 v[10:11], v[10:11], 0, v[214:215]
	v_mad_i64_i32 v[12:13], s[24:25], v12, s79, v[34:35]
	v_min_u32_e32 v18, s36, v18
	v_add_co_u32_e32 v10, vcc, s88, v10
	v_lshl_add_u64 v[12:13], v[12:13], 0, s[84:85]
	v_lshl_add_u32 v18, v18, 6, v37
	v_add_u32_e32 v20, 5, v36
	v_addc_co_u32_e32 v11, vcc, 0, v11, vcc
	v_lshl_add_u64 v[12:13], v[12:13], 0, v[214:215]
	v_mad_i64_i32 v[18:19], s[24:25], v18, s79, v[34:35]
	v_min_u32_e32 v20, s36, v20
	v_add_co_u32_e32 v14, vcc, s88, v12
	v_lshl_add_u64 v[18:19], v[18:19], 0, s[84:85]
	v_lshl_add_u32 v20, v20, 6, v37
	v_add_u32_e32 v26, 6, v36
	v_addc_co_u32_e32 v15, vcc, 0, v13, vcc
	v_lshl_add_u64 v[18:19], v[18:19], 0, v[214:215]
	v_mad_i64_i32 v[20:21], s[24:25], v20, s79, v[34:35]
	v_min_u32_e32 v26, s36, v26
	v_add_co_u32_e32 v18, vcc, s88, v18
	v_lshl_add_u64 v[20:21], v[20:21], 0, s[84:85]
	v_lshl_add_u32 v26, v26, 6, v37
	v_add_u32_e32 v28, 7, v36
	v_addc_co_u32_e32 v19, vcc, 0, v19, vcc
	v_lshl_add_u64 v[20:21], v[20:21], 0, v[214:215]
	v_mad_i64_i32 v[26:27], s[24:25], v26, s79, v[34:35]
	v_min_u32_e32 v28, s36, v28
	v_add_co_u32_e32 v22, vcc, s88, v20
	v_lshl_add_u64 v[26:27], v[26:27], 0, s[84:85]
	v_lshl_add_u32 v28, v28, 6, v37
	v_add_u32_e32 v36, 8, v36
	v_addc_co_u32_e32 v23, vcc, 0, v21, vcc
	v_lshl_add_u64 v[26:27], v[26:27], 0, v[214:215]
	v_mad_i64_i32 v[28:29], s[24:25], v28, s79, v[34:35]
	v_min_u32_e32 v36, s36, v36
	v_add_co_u32_e32 v26, vcc, s88, v26
	v_lshl_add_u64 v[28:29], v[28:29], 0, s[84:85]
	v_lshl_add_u32 v36, v36, 6, v37
	v_addc_co_u32_e32 v27, vcc, 0, v27, vcc
	v_lshl_add_u64 v[28:29], v[28:29], 0, v[214:215]
	v_mad_i64_i32 v[34:35], s[24:25], v36, s79, v[34:35]
	v_add_co_u32_e32 v30, vcc, s88, v28
	v_lshl_add_u64 v[34:35], v[34:35], 0, s[84:85]
	s_nop 0
	v_addc_co_u32_e32 v31, vcc, 0, v29, vcc
	v_lshl_add_u64 v[34:35], v[34:35], 0, v[214:215]
	v_add_co_u32_e32 v34, vcc, 0x2000, v34
	v_mov_b32_e32 v100, v2
	v_mov_b32_e32 v101, v3
	global_load_dwordx4 v[2:5], v[2:3], off
	s_nop 0
	global_load_dwordx4 v[6:9], v[6:7], off
	v_addc_co_u32_e32 v35, vcc, 0, v35, vcc
	global_load_dwordx4 v[10:13], v[10:11], off
	s_nop 0
	global_load_dwordx4 v[14:17], v[14:15], off
	s_nop 0
	global_load_dwordx4 v[18:21], v[18:19], off
	s_nop 0
	global_load_dwordx4 v[22:25], v[22:23], off
	s_nop 0
	global_load_dwordx4 v[26:29], v[26:27], off
	s_nop 0
	global_load_dwordx4 v[30:33], v[30:31], off
	s_cmp_lt_i32 s13, 1
	v_mov_b32_e32 v108, v34
	v_mov_b32_e32 v109, v35
	global_load_dwordx4 v[34:37], v[34:35], off
	s_mov_b32 s86, s13
	s_cbranch_scc1 .LBB0_491
	s_cmp_eq_u32 s13, 1
	s_mov_b64 s[86:87], -1
	s_cbranch_scc1 .LBB0_489
	s_mov_b64 s[86:87], 0

; __device__ __forceinline__ void c_prefetch(const bf16* P, int un, int tid, int wave, int fr, int fq, v4u (&vpre)[9], bf16x8& Q0, bf16x8& Q1, bf16x8 (&K)[8][2]) {
;     ...
;     const int r = rf + (wave >> 2), j = wave & 3;
;     int rs = r - 4; rs = rs < 0 ? 0 : rs; rs = rs > rows - 8 ? rows - 8 : rs;
;     const int kcol0 = j == 0 ? 0 : (j == 1 ? 8 : (j == 2 ? 24 : 32));
;     { const bf16* qp = P + (size_t)(s0 + r * 64 + 16 * j + fr) * DIN + C_QC + h * 64 + fq * 8; Q0 = *(const bf16x8*)qp; Q1 = *(const bf16x8*)(qp + 32); }
; #pragma unroll
;     for (int kt = 0; kt < 8; ++kt) { const bf16* kp = P + (size_t)(s0 + (rs + (kt >> 1)) * 64 + kcol0 + 16 * (kt & 1) + fr) * DIN + C_KC + h * 64 + fq * 8;
;         K[kt][0] = *(const bf16x8*)kp; K[kt][1] = *(const bf16x8*)(kp + 32); }
.LBB0_491:
	s_add_i32 s27, s27, s12
	s_max_i32 s24, s27, 4
	s_add_i32 s24, s24, -4
	s_min_u32 s36, s24, s93
	s_lshl_b32 s24, s27, 6
	s_add_i32 s24, s24, s26
	v_or_b32_e32 v38, s24, v1
	v_mov_b64_e32 v[102:103], s[74:75]
	v_mad_i64_i32 v[38:39], s[24:25], v38, s79, v[102:103]
	v_or_b32_e32 v46, s26, v207
	v_lshl_add_u64 v[38:39], v[38:39], 0, s[84:85]
	v_add_u32_e32 v94, s86, v46
	s_lshl_b32 s26, s36, 6
	v_lshl_add_u64 v[38:39], v[38:39], 0, v[210:211]
	s_mov_b64 s[24:25], 0x1a00
	v_add_u32_e32 v46, s26, v94
	v_lshl_add_u64 v[42:43], v[38:39], 0, s[24:25]
	v_mad_i64_i32 v[46:47], s[24:25], v46, s79, v[102:103]
	v_add_u32_e32 v104, 16, v94
	v_add_co_u32_e32 v38, vcc, 0x1000, v38
	v_lshl_add_u64 v[46:47], v[46:47], 0, s[84:85]
	v_add_u32_e32 v54, s26, v104
	v_addc_co_u32_e32 v39, vcc, 0, v39, vcc
	v_lshl_add_u64 v[46:47], v[46:47], 0, v[210:211]
	v_mad_i64_i32 v[54:55], s[24:25], v54, s79, v[102:103]
	s_add_i32 s27, s26, 64
	v_lshl_add_u64 v[50:51], v[46:47], 0, s[22:23]
	v_add_co_u32_e32 v46, vcc, s88, v46
	v_lshl_add_u64 v[54:55], v[54:55], 0, s[84:85]
	v_add_u32_e32 v62, s27, v94
	v_addc_co_u32_e32 v47, vcc, 0, v47, vcc
	v_lshl_add_u64 v[54:55], v[54:55], 0, v[210:211]
	v_mad_i64_i32 v[62:63], s[24:25], v62, s79, v[102:103]
	v_lshl_add_u64 v[58:59], v[54:55], 0, s[22:23]
	v_add_co_u32_e32 v54, vcc, s88, v54
	v_lshl_add_u64 v[62:63], v[62:63], 0, s[84:85]
	v_add_u32_e32 v70, s27, v104
	v_addc_co_u32_e32 v55, vcc, 0, v55, vcc
	v_lshl_add_u64 v[62:63], v[62:63], 0, v[210:211]
	v_mad_i64_i32 v[70:71], s[24:25], v70, s79, v[102:103]
	s_add_i32 s27, s26, 0x80
	v_lshl_add_u64 v[66:67], v[62:63], 0, s[22:23]
	v_add_co_u32_e32 v62, vcc, s88, v62
	v_lshl_add_u64 v[70:71], v[70:71], 0, s[84:85]
	v_add_u32_e32 v78, s27, v94
	v_addc_co_u32_e32 v63, vcc, 0, v63, vcc
	v_lshl_add_u64 v[70:71], v[70:71], 0, v[210:211]
	v_mad_i64_i32 v[78:79], s[24:25], v78, s79, v[102:103]
	v_lshl_add_u64 v[74:75], v[70:71], 0, s[22:23]
	v_add_co_u32_e32 v70, vcc, s88, v70
	v_lshl_add_u64 v[78:79], v[78:79], 0, s[84:85]
	v_add_u32_e32 v86, s27, v104
	v_addc_co_u32_e32 v71, vcc, 0, v71, vcc
	v_lshl_add_u64 v[78:79], v[78:79], 0, v[210:211]
	v_mad_i64_i32 v[86:87], s[24:25], v86, s79, v[102:103]
	s_addk_i32 s26, 0xc0
	v_lshl_add_u64 v[80:81], v[78:79], 0, s[22:23]
	v_add_co_u32_e32 v78, vcc, s88, v78
	v_lshl_add_u64 v[86:87], v[86:87], 0, s[84:85]
	v_add_u32_e32 v94, s26, v94
	v_addc_co_u32_e32 v79, vcc, 0, v79, vcc
	v_lshl_add_u64 v[86:87], v[86:87], 0, v[210:211]
	v_mad_i64_i32 v[94:95], s[24:25], v94, s79, v[102:103]
	v_lshl_add_u64 v[90:91], v[86:87], 0, s[22:23]
	v_add_co_u32_e32 v86, vcc, s88, v86
	v_lshl_add_u64 v[94:95], v[94:95], 0, s[84:85]
	v_add_u32_e32 v104, s26, v104
	v_addc_co_u32_e32 v87, vcc, 0, v87, vcc
	v_lshl_add_u64 v[94:95], v[94:95], 0, v[210:211]
	v_mad_i64_i32 v[102:103], s[24:25], v104, s79, v[102:103]
	v_lshl_add_u64 v[98:99], v[94:95], 0, s[22:23]
	v_add_co_u32_e32 v94, vcc, s88, v94
	v_lshl_add_u64 v[102:103], v[102:103], 0, s[84:85]
	s_nop 0
	v_addc_co_u32_e32 v95, vcc, 0, v95, vcc
	v_lshl_add_u64 v[102:103], v[102:103], 0, v[210:211]
	v_lshl_add_u64 v[106:107], v[102:103], 0, s[22:23]
	v_add_co_u32_e32 v102, vcc, 0x2000, v102
	global_load_dwordx4 v[38:41], v[38:39], off offset:2560
	s_nop 0
	global_load_dwordx4 v[42:45], v[42:43], off offset:64
	v_addc_co_u32_e32 v103, vcc, 0, v103, vcc
	s_nop 0
	s_nop 0
	s_nop 0
	s_nop 0
	s_nop 0
	s_nop 0
	s_nop 0
	s_nop 0
	s_nop 0
	s_nop 0
	s_nop 0
	s_nop 0
	s_nop 0
	s_nop 0
	s_nop 0
	s_nop 0
	s_nop 0
	s_nop 0
	s_nop 0
	s_nop 0
	s_nop 0
	s_nop 0
	s_nop 0
	s_nop 0
	s_nop 0
	s_nop 0
	s_nop 0
	s_nop 0
	s_nop 0
	s_nop 0
	s_nop 0
	v_mov_b32_e32 v138, 0xf149f2ca
	v_mov_b32_e32 v139, 0xf149f2ca
	s_and_saveexec_b64 s[84:85], s[0:1]
	s_cbranch_execz .LBB0_424

; __device__ __forceinline__ void seq_of(int row, int& s0, int& T) { if (row < MP) { s0 = row & ~2047; T = 2048; } else { s0 = MP + ((row - MP) & ~4095); T = 4096; } }
; __device__ __forceinline__ void c_prefetch(const bf16* P, int un, int tid, int wave, int fr, int fq, v4u (&vpre)[9], bf16x8& Q0, bf16x8& Q1, bf16x8 (&K)[8][2]) {
;     const int h = un / (M / 128), blk = un - h * (M / 128), row0 = blk * 128; int s0, T; seq_of(row0, s0, T);
;     const int rows = T >> 6, rf = (row0 - s0) >> 6;
;     int R0 = rf - 4; R0 = R0 < 0 ? 0 : R0; R0 = R0 > rows - 8 ? rows - 8 : R0;
; #pragma unroll
;     for (int i = 0; i < 9; ++i) { const int e = tid + i * NTHREADS, key = e >> 3, chunk = e & 7; int gr = R0 + (key >> 6); gr = gr > rows - 1 ? rows - 1 : gr;
;         vpre[i] = *(const v4u*)(P + (size_t)(s0 + gr * 64 + (key & 63)) * DIN + C_VC + h * 64 + chunk * 8); }
; __device__ __forceinline__ void mixC_mfma(const bf16* P, const float* rpb  , bf16* MIX, LAS unsigned char* lds, int bid, int G, int tid) {
;     ...
;     const int vb_ = (G % 8 == 0) ? (bid & 7) * (G >> 3) + (bid >> 3) : bid;
;     if (vb_ < NU) c_prefetch(P, vb_, tid, wave, fr, fq, vpre, Qn0, Qn1, Kn);
.LBB0_1368:
	s_cmpk_lt_i32 s12, 0x900
	s_cselect_b64 s[0:1], -1, 0
	s_cmpk_gt_i32 s12, 0x8ff
	v_bfe_u32 v110, v208, 4, 2
	s_cbranch_scc1 .LBB0_1372
	s_mul_hi_i32 s4, s12, 0x2aaaaaab
	s_lshr_b32 s5, s4, 31
	s_ashr_i32 s4, s4, 5
	s_add_i32 s4, s4, s5
	s_mul_i32 s5, s4, 0xffffff40
	s_add_i32 s5, s5, s12
	s_lshl_b32 s6, s5, 7
	s_cmpk_lt_i32 s5, 0x80
	s_movk_i32 s5, 0xf800
	s_cselect_b32 s5, s5, 0x7ffff000
	s_cselect_b32 s7, 32, 64
	s_and_b32 s11, s5, s6
	s_sub_i32 s5, s6, s11
	s_ashr_i32 s13, s5, 6
	s_max_i32 s5, s13, 4
	s_add_i32 s5, s5, -4
	s_add_i32 s14, s7, -8
	s_min_u32 s5, s5, s14
	v_lshrrev_b32_e32 v1, 3, v208
	v_add_u32_e32 v36, s5, v207
	s_add_i32 s15, s7, -1
	v_and_or_b32 v1, v1, 63, s11
	s_lshl_b32 s4, s4, 6
	v_min_u32_e32 v2, s15, v36
	v_lshlrev_b32_e32 v4, 4, v208
	s_ashr_i32 s5, s4, 31
	v_lshl_add_u32 v2, v2, 6, v1
	s_movk_i32 s9, 0x2c00
	v_mov_b64_e32 v[34:35], s[74:75]
	v_and_b32_e32 v102, 0x70, v4
	v_add_u32_e32 v4, 1, v36
	v_mad_i64_i32 v[2:3], s[6:7], v2, s9, v[34:35]
	s_lshl_b64 s[4:5], s[4:5], 1
	v_min_u32_e32 v4, s15, v4
	v_lshl_add_u64 v[2:3], v[2:3], 0, s[4:5]
	v_mov_b32_e32 v103, 0
	v_lshl_add_u32 v4, v4, 6, v1
	v_add_u32_e32 v10, 2, v36
	v_lshl_add_u64 v[2:3], v[2:3], 0, v[102:103]
	s_movk_i32 s10, 0x2000
	v_mad_i64_i32 v[4:5], s[6:7], v4, s9, v[34:35]
	v_min_u32_e32 v10, s15, v10
	v_add_co_u32_e32 v2, vcc, s10, v2
	v_lshl_add_u64 v[4:5], v[4:5], 0, s[4:5]
	v_lshl_add_u32 v10, v10, 6, v1
	v_add_u32_e32 v12, 3, v36
	v_addc_co_u32_e32 v3, vcc, 0, v3, vcc
	v_lshl_add_u64 v[4:5], v[4:5], 0, v[102:103]
	v_mad_i64_i32 v[10:11], s[6:7], v10, s9, v[34:35]
	v_min_u32_e32 v12, s15, v12
	v_add_co_u32_e32 v6, vcc, s10, v4
	v_lshl_add_u64 v[10:11], v[10:11], 0, s[4:5]
	v_lshl_add_u32 v12, v12, 6, v1
	v_add_u32_e32 v18, 4, v36
	v_addc_co_u32_e32 v7, vcc, 0, v5, vcc
	v_lshl_add_u64 v[10:11], v[10:11], 0, v[102:103]
	v_mad_i64_i32 v[12:13], s[6:7], v12, s9, v[34:35]
	v_min_u32_e32 v18, s15, v18
	v_add_co_u32_e32 v10, vcc, s10, v10
	v_lshl_add_u64 v[12:13], v[12:13], 0, s[4:5]
	v_lshl_add_u32 v18, v18, 6, v1
	v_add_u32_e32 v20, 5, v36
	v_addc_co_u32_e32 v11, vcc, 0, v11, vcc
	v_lshl_add_u64 v[12:13], v[12:13], 0, v[102:103]
	v_mad_i64_i32 v[18:19], s[6:7], v18, s9, v[34:35]
	v_min_u32_e32 v20, s15, v20
	v_add_co_u32_e32 v14, vcc, s10, v12
	v_lshl_add_u64 v[18:19], v[18:19], 0, s[4:5]
	v_lshl_add_u32 v20, v20, 6, v1
	v_add_u32_e32 v26, 6, v36
	v_addc_co_u32_e32 v15, vcc, 0, v13, vcc
	v_lshl_add_u64 v[18:19], v[18:19], 0, v[102:103]
	v_mad_i64_i32 v[20:21], s[6:7], v20, s9, v[34:35]
	v_min_u32_e32 v26, s15, v26
	v_add_co_u32_e32 v18, vcc, s10, v18
	v_lshl_add_u64 v[20:21], v[20:21], 0, s[4:5]
	v_lshl_add_u32 v26, v26, 6, v1
	v_add_u32_e32 v28, 7, v36
	v_addc_co_u32_e32 v19, vcc, 0, v19, vcc
	v_lshl_add_u64 v[20:21], v[20:21], 0, v[102:103]
	v_mad_i64_i32 v[26:27], s[6:7], v26, s9, v[34:35]
	v_min_u32_e32 v28, s15, v28
	v_add_co_u32_e32 v22, vcc, s10, v20
	v_lshl_add_u64 v[26:27], v[26:27], 0, s[4:5]
	v_lshl_add_u32 v28, v28, 6, v1
	v_add_u32_e32 v36, 8, v36
	v_addc_co_u32_e32 v23, vcc, 0, v21, vcc
	v_lshl_add_u64 v[26:27], v[26:27], 0, v[102:103]
	v_mad_i64_i32 v[28:29], s[6:7], v28, s9, v[34:35]
	v_min_u32_e32 v36, s15, v36
	v_add_co_u32_e32 v26, vcc, s10, v26
	v_lshl_add_u64 v[28:29], v[28:29], 0, s[4:5]
	v_lshl_add_u32 v1, v36, 6, v1
	v_addc_co_u32_e32 v27, vcc, 0, v27, vcc
	v_lshl_add_u64 v[28:29], v[28:29], 0, v[102:103]
	v_mad_i64_i32 v[34:35], s[6:7], v1, s9, v[34:35]
	v_add_co_u32_e32 v30, vcc, s10, v28
	v_lshl_add_u64 v[34:35], v[34:35], 0, s[4:5]
	s_nop 0
	v_addc_co_u32_e32 v31, vcc, 0, v29, vcc
	v_lshl_add_u64 v[34:35], v[34:35], 0, v[102:103]
	v_add_co_u32_e32 v34, vcc, 0x2000, v34
	v_mov_b32_e32 v100, v2
	v_mov_b32_e32 v101, v3
	global_load_dwordx4 v[2:5], v[2:3], off
	s_nop 0
	global_load_dwordx4 v[6:9], v[6:7], off
	v_addc_co_u32_e32 v35, vcc, 0, v35, vcc
	global_load_dwordx4 v[10:13], v[10:11], off
	s_nop 0
	global_load_dwordx4 v[14:17], v[14:15], off
	s_nop 0
	global_load_dwordx4 v[18:21], v[18:19], off
	s_nop 0
	global_load_dwordx4 v[22:25], v[22:23], off
	s_nop 0
	global_load_dwordx4 v[26:29], v[26:27], off
	s_nop 0
	global_load_dwordx4 v[30:33], v[30:31], off
	s_bfe_u32 s16, s8, 0x20006
	v_mov_b32_e32 v108, v34
	v_mov_b32_e32 v109, v35
	global_load_dwordx4 v[34:37], v[34:35], off
	s_cmp_lt_i32 s16, 1
	s_mov_b32 s15, s16
	s_cbranch_scc1 .LBB0_1375
	s_cmp_eq_u32 s16, 1
	s_cbranch_scc1 .LBB0_1373
	s_cmp_eq_u32 s16, 2
	s_cselect_b32 s15, 24, 32
	s_cbranch_execz .LBB0_1374
	s_branch .LBB0_1375

; __device__ __forceinline__ void c_prefetch(const bf16* P, int un, int tid, int wave, int fr, int fq, v4u (&vpre)[9], bf16x8& Q0, bf16x8& Q1, bf16x8 (&K)[8][2]) {
;     ...
;     const int r = rf + (wave >> 2), j = wave & 3;
;     int rs = r - 4; rs = rs < 0 ? 0 : rs; rs = rs > rows - 8 ? rows - 8 : rs;
;     const int kcol0 = j == 0 ? 0 : (j == 1 ? 8 : (j == 2 ? 24 : 32));
;     { const bf16* qp = P + (size_t)(s0 + r * 64 + 16 * j + fr) * DIN + C_QC + h * 64 + fq * 8; Q0 = *(const bf16x8*)qp; Q1 = *(const bf16x8*)(qp + 32); }
; #pragma unroll
;     for (int kt = 0; kt < 8; ++kt) { const bf16* kp = P + (size_t)(s0 + (rs + (kt >> 1)) * 64 + kcol0 + 16 * (kt & 1) + fr) * DIN + C_KC + h * 64 + fq * 8;
;         K[kt][0] = *(const bf16x8*)kp; K[kt][1] = *(const bf16x8*)(kp + 32); }
.LBB0_1375:
	s_lshr_b32 s6, s8, 8
	s_add_i32 s13, s13, s6
	s_max_i32 s6, s13, 4
	s_add_i32 s6, s6, -4
	s_min_u32 s14, s6, s14
	s_lshl_b32 s6, s13, 6
	s_add_i32 s6, s6, s11
	s_lshl_b32 s7, s16, 4
	s_or_b32 s6, s6, s7
	v_or_b32_e32 v1, s6, v213
	v_mov_b64_e32 v[104:105], s[74:75]
	v_mad_i64_i32 v[38:39], s[6:7], v1, s9, v[104:105]
	v_lshl_add_u64 v[38:39], v[38:39], 0, s[4:5]
	v_lshlrev_b32_e32 v102, 4, v110
	v_or_b32_e32 v1, s11, v213
	v_lshl_add_u64 v[38:39], v[38:39], 0, v[102:103]
	s_mov_b64 s[6:7], 0x1a00
	v_add_u32_e32 v1, s15, v1
	s_lshl_b32 s11, s14, 6
	v_lshl_add_u64 v[42:43], v[38:39], 0, s[6:7]
	s_movk_i32 s6, 0x1000
	v_add_u32_e32 v46, s11, v1
	v_add_co_u32_e32 v38, vcc, s6, v38
	v_mad_i64_i32 v[46:47], s[6:7], v46, s9, v[104:105]
	v_add_u32_e32 v106, 16, v1
	v_lshl_add_u64 v[46:47], v[46:47], 0, s[4:5]
	v_add_u32_e32 v54, s11, v106
	v_addc_co_u32_e32 v39, vcc, 0, v39, vcc
	v_lshl_add_u64 v[46:47], v[46:47], 0, v[102:103]
	s_mov_b64 s[6:7], 0x2000
	v_mad_i64_i32 v[54:55], s[14:15], v54, s9, v[104:105]
	s_add_i32 s13, s11, 64
	v_lshl_add_u64 v[50:51], v[46:47], 0, s[6:7]
	v_add_co_u32_e32 v46, vcc, s10, v46
	v_lshl_add_u64 v[54:55], v[54:55], 0, s[4:5]
	v_add_u32_e32 v62, s13, v1
	v_addc_co_u32_e32 v47, vcc, 0, v47, vcc
	v_lshl_add_u64 v[54:55], v[54:55], 0, v[102:103]
	v_mad_i64_i32 v[62:63], s[14:15], v62, s9, v[104:105]
	v_lshl_add_u64 v[58:59], v[54:55], 0, s[6:7]
	v_add_co_u32_e32 v54, vcc, s10, v54
	v_lshl_add_u64 v[62:63], v[62:63], 0, s[4:5]
	v_add_u32_e32 v70, s13, v106
	v_addc_co_u32_e32 v55, vcc, 0, v55, vcc
	v_lshl_add_u64 v[62:63], v[62:63], 0, v[102:103]
	v_mad_i64_i32 v[70:71], s[14:15], v70, s9, v[104:105]
	s_add_i32 s13, s11, 0x80
	v_lshl_add_u64 v[66:67], v[62:63], 0, s[6:7]
	v_add_co_u32_e32 v62, vcc, s10, v62
	v_lshl_add_u64 v[70:71], v[70:71], 0, s[4:5]
	v_add_u32_e32 v78, s13, v1
	v_addc_co_u32_e32 v63, vcc, 0, v63, vcc
	v_lshl_add_u64 v[70:71], v[70:71], 0, v[102:103]
	v_mad_i64_i32 v[78:79], s[14:15], v78, s9, v[104:105]
	v_lshl_add_u64 v[74:75], v[70:71], 0, s[6:7]
	v_add_co_u32_e32 v70, vcc, s10, v70
	v_lshl_add_u64 v[78:79], v[78:79], 0, s[4:5]
	v_add_u32_e32 v86, s13, v106
	v_addc_co_u32_e32 v71, vcc, 0, v71, vcc
	v_lshl_add_u64 v[78:79], v[78:79], 0, v[102:103]
	v_mad_i64_i32 v[86:87], s[14:15], v86, s9, v[104:105]
	s_addk_i32 s11, 0xc0
	v_lshl_add_u64 v[80:81], v[78:79], 0, s[6:7]
	v_add_co_u32_e32 v78, vcc, s10, v78
	v_lshl_add_u64 v[86:87], v[86:87], 0, s[4:5]
	v_add_u32_e32 v1, s11, v1
	v_addc_co_u32_e32 v79, vcc, 0, v79, vcc
	v_lshl_add_u64 v[86:87], v[86:87], 0, v[102:103]
	v_mad_i64_i32 v[94:95], s[14:15], v1, s9, v[104:105]
	v_lshl_add_u64 v[90:91], v[86:87], 0, s[6:7]
	v_add_co_u32_e32 v86, vcc, s10, v86
	v_lshl_add_u64 v[94:95], v[94:95], 0, s[4:5]
	s_nop 0
	v_addc_co_u32_e32 v87, vcc, 0, v87, vcc
	v_lshl_add_u64 v[94:95], v[94:95], 0, v[102:103]
	v_add_u32_e32 v1, s11, v106
	v_lshl_add_u64 v[98:99], v[94:95], 0, s[6:7]
	v_add_co_u32_e32 v94, vcc, s10, v94
	v_mad_i64_i32 v[104:105], s[10:11], v1, s9, v[104:105]
	v_lshl_add_u64 v[104:105], v[104:105], 0, s[4:5]
	v_addc_co_u32_e32 v95, vcc, 0, v95, vcc
	v_lshl_add_u64 v[102:103], v[104:105], 0, v[102:103]
	v_lshl_add_u64 v[106:107], v[102:103], 0, s[6:7]
	v_add_co_u32_e32 v102, vcc, 0x2000, v102
	global_load_dwordx4 v[38:41], v[38:39], off offset:2560
	s_nop 0
	global_load_dwordx4 v[42:45], v[42:43], off offset:64
	v_addc_co_u32_e32 v103, vcc, 0, v103, vcc
	s_nop 0
	s_nop 0
	s_nop 0
	s_nop 0
	s_nop 0
	s_nop 0
	s_nop 0
	s_nop 0
	s_nop 0
	s_nop 0
	s_nop 0
	s_nop 0
	s_nop 0
	s_nop 0
	s_nop 0
	s_nop 0
	s_nop 0
	s_nop 0
	s_nop 0
	s_nop 0
	s_nop 0
	s_nop 0
	s_nop 0
	s_nop 0
	s_nop 0
	s_nop 0
	s_nop 0
	s_nop 0
	s_nop 0
	s_nop 0
	s_nop 0
	s_andn2_b64 vcc, exec, s[0:1]
	s_cbranch_vccnz .LBB0_1518

; #define LAS __attribute__((address_space(3)))
; __device__ __forceinline__ void seq_of(int row, int& s0, int& T) { if (row < MP) { s0 = row & ~2047; T = 2048; } else { s0 = MP + ((row - MP) & ~4095); T = 4096; } }
; __device__ __forceinline__ void mixC_mfma(const bf16* P, const float* rpb  , bf16* MIX, LAS unsigned char* lds, int bid, int G, int tid) {
;     ...
;     for (int un = vb_; un < NU; un += G) {
;         const int h = un / (M / 128), blk = un - h * (M / 128), row0 = blk * 128; int s0, T; seq_of(row0, s0, T);
;         const int rows = T >> 6, rf = (row0 - s0) >> 6;
;         int R0 = rf - 4; R0 = R0 < 0 ? 0 : R0; R0 = R0 > rows - 8 ? rows - 8 : R0;
;         __syncthreads();
; #pragma unroll
;         for (int i = 0; i < 9; ++i) { const int e = tid + i * NTHREADS; *(LAS v4u*)(Vs + (e >> 3) * VROW + (e & 7) * 16) = vpre[i]; }
;         __syncthreads();
.LBB0_1378:
	s_mul_hi_i32 s0, s12, 0x2aaaaaab
	s_lshr_b32 s1, s0, 31
	s_ashr_i32 s4, s0, 5
	s_add_i32 s4, s4, s1
	s_mul_i32 s0, s4, 0xffffff40
	s_mul_i32 s1, s4, 0xffffa000
	s_add_i32 s0, s12, s0
	s_add_i32 s1, s57, s1
	s_cmpk_lt_i32 s0, 0x80
	s_cselect_b32 s0, s78, 0x7ffff000
	s_cselect_b32 s5, 24, 56
	s_and_b32 s82, s0, s1
	s_mul_i32 s0, s4, 0x6000
	s_add_i32 s0, s82, s0
	s_sub_i32 s0, s57, s0
	s_ashr_i32 s83, s0, 6
	s_max_i32 s0, s83, 4
	s_add_i32 s0, s0, -4
	s_min_u32 s84, s0, s5
	s_cmp_lt_i32 s33, 1
	s_mov_b32 s85, s33
	s_waitcnt lgkmcnt(0)
	s_barrier
	s_waitcnt vmcnt(10)
	ds_write_b128 v223, v[2:5]
	s_waitcnt vmcnt(9)
	ds_write_b128 v226, v[6:9]
	s_waitcnt vmcnt(8)
	ds_write_b128 v223, v[10:13] offset:20480
	s_waitcnt vmcnt(7)
	ds_write_b128 v227, v[14:17]
	s_waitcnt vmcnt(6)
	ds_write_b128 v223, v[18:21] offset:40960
	s_waitcnt vmcnt(5)
	ds_write_b128 v228, v[22:25]
	s_waitcnt vmcnt(4)
	ds_write_b128 v223, v[26:29] offset:61440
	s_waitcnt vmcnt(3)
	ds_write_b128 v229, v[30:33]
	s_waitcnt vmcnt(2)
	ds_write_b128 v224, v[34:37]
	s_waitcnt lgkmcnt(0)
	s_barrier
	v_mov_b32_e32 v252, 0xb0000
	v_mov_b32_e32 v253, 0
	v_lshl_add_u64 v[6:7], v[100:101], 0, v[252:253]
	v_lshl_add_u64 v[10:11], v[6:7], 0, v[252:253]
	v_lshl_add_u64 v[14:15], v[10:11], 0, v[252:253]
	v_lshl_add_u64 v[18:19], v[14:15], 0, v[252:253]
	v_lshl_add_u64 v[22:23], v[18:19], 0, v[252:253]
	v_lshl_add_u64 v[26:27], v[22:23], 0, v[252:253]
	v_lshl_add_u64 v[30:31], v[26:27], 0, v[252:253]
	v_mov_b32_e32 v34, v108
	v_mov_b32_e32 v35, v109
	v_mov_b32_e32 v2, v100
	v_mov_b32_e32 v3, v101
	global_load_dwordx4 v[2:5], v[2:3], off offset:1536
	global_load_dwordx4 v[6:9], v[6:7], off offset:1536
	global_load_dwordx4 v[10:13], v[10:11], off offset:1536
	global_load_dwordx4 v[14:17], v[14:15], off offset:1536
	global_load_dwordx4 v[18:21], v[18:19], off offset:1536
	global_load_dwordx4 v[22:25], v[22:23], off offset:1536
	global_load_dwordx4 v[26:29], v[26:27], off offset:1536
	global_load_dwordx4 v[30:33], v[30:31], off offset:1536
	global_load_dwordx4 v[34:37], v[34:35], off offset:1536
	s_cbranch_scc1 .LBB0_1383
	s_cmp_eq_u32 s33, 1
	s_mov_b64 s[0:1], -1
	s_cbranch_scc1 .LBB0_1381
	s_mov_b64 s[0:1], 0

; __device__ __forceinline__ void mixC_mfma(const bf16* P, const float* rpb  , bf16* MIX, LAS unsigned char* lds, int bid, int G, int tid) {
;     ...
;         const int r = rf + (wave >> 2), j = wave & 3;
;         int rs = r - 4; rs = rs < 0 ? 0 : rs; rs = rs > rows - 8 ? rows - 8 : rs;
;         const int kcol0 = j == 0 ? 0 : (j == 1 ? 8 : (j == 2 ? 24 : 32));
;         const int c = 16 * j + fr; int cs = c - 8; cs = cs < 0 ? 0 : cs; cs = cs > 48 ? 48 : cs;
;         const size_t qrow = (size_t)(s0 + r * 64 + c);
;         f32x4 S[16];
;         bf16x8 Kl[8][2];
; #pragma unroll
;         for (int kt = 8; kt < 16; ++kt) { const bf16* kp = P + (size_t)(s0 + (rs + (kt >> 1)) * 64 + kcol0 + 16 * (kt & 1) + fr) * DIN + C_KC + h * 64 + fq * 8;
;             Kl[kt - 8][0] = *(const bf16x8*)kp; Kl[kt - 8][1] = *(const bf16x8*)(kp + 32); }
; #pragma unroll
;         for (int kt = 0; kt < 8; ++kt) { f32x4 z = {0.f, 0.f, 0.f, 0.f};
;             z = __builtin_amdgcn_mfma_f32_16x16x32_bf16(Kn[kt][0], Qn0, z, 0, 0, 0);
;             S[kt] = __builtin_amdgcn_mfma_f32_16x16x32_bf16(Kn[kt][1], Qn1, z, 0, 0, 0); }
.LBB0_1383:
	s_add_i32 s83, s83, s13
	s_max_i32 s0, s83, 4
	s_add_i32 s0, s0, -4
	s_min_u32 s86, s0, s5
	v_mov_b32_e32 v253, s84
	v_sub_u32_e32 v253, s86, v253
	v_lshl_add_u32 v253, v253, 6, s85
	v_mul_u32_u24_e32 v253, 0xa0, v253
	v_and_b32_e32 v255, 15, v208
	v_mul_u32_u24_e32 v255, 0xa0, v255
	v_bfe_u32 v254, v208, 4, 2
	v_lshl_add_u32 v255, v254, 4, v255
	v_add_u32_e32 v255, v253, v255
	v_add_u32_e32 v254, 0xa000, v255
	ds_read_b128 v[46:49], v255
	ds_read_b128 v[50:53], v255 offset:64
	ds_read_b128 v[54:57], v255 offset:2560
	ds_read_b128 v[58:61], v255 offset:2624
	ds_read_b128 v[62:65], v255 offset:10240
	ds_read_b128 v[66:69], v255 offset:10304
	ds_read_b128 v[70:73], v255 offset:12800
	ds_read_b128 v[74:77], v255 offset:12864
	ds_read_b128 v[82:85], v255 offset:20480
	ds_read_b128 v[78:81], v255 offset:20544
	ds_read_b128 v[86:89], v255 offset:23040
	ds_read_b128 v[90:93], v255 offset:23104
	ds_read_b128 v[94:97], v255 offset:30720
	ds_read_b128 v[98:101], v255 offset:30784
	ds_read_b128 v[102:105], v255 offset:33280
	ds_read_b128 v[106:109], v255 offset:33344
	s_waitcnt lgkmcnt(0)
	v_or_b32_e32 v110, s82, v213
	s_lshl_b32 s5, s86, 6
	v_add_u32_e32 v162, s85, v110
	s_add_i32 s6, s5, 0x100
	s_lshl_b32 s24, s4, 6
	v_add_u32_e32 v110, s6, v162
	v_mov_b64_e32 v[170:171], s[74:75]
	s_ashr_i32 s25, s24, 31
	v_mad_i64_i32 v[110:111], s[0:1], v110, s79, v[170:171]
	s_lshl_b64 s[0:1], s[24:25], 1
	v_add_u32_e32 v172, 16, v162
	v_lshl_add_u64 v[110:111], v[110:111], 0, s[0:1]
	v_add_u32_e32 v118, s6, v172
	v_lshl_add_u64 v[110:111], v[110:111], 0, v[210:211]
	v_mad_i64_i32 v[118:119], s[6:7], v118, s79, v[170:171]
	s_add_i32 s8, s5, 0x140
	s_waitcnt vmcnt(9)
	v_mfma_f32_16x16x32_bf16 v[142:145], v[46:49], v[38:41], 0
	v_lshl_add_u64 v[114:115], v[110:111], 0, s[20:21]
	v_add_co_u32_e32 v110, vcc, s80, v110
	v_lshl_add_u64 v[118:119], v[118:119], 0, s[0:1]
	v_add_u32_e32 v126, s8, v162
	v_addc_co_u32_e32 v111, vcc, 0, v111, vcc
	v_lshl_add_u64 v[118:119], v[118:119], 0, v[210:211]
	v_mad_i64_i32 v[126:127], s[6:7], v126, s79, v[170:171]
	v_lshl_add_u64 v[122:123], v[118:119], 0, s[20:21]
	v_add_co_u32_e32 v118, vcc, s80, v118
	v_lshl_add_u64 v[126:127], v[126:127], 0, s[0:1]
	v_add_u32_e32 v134, s8, v172
	s_add_i32 s8, s5, 0x180
	v_addc_co_u32_e32 v119, vcc, 0, v119, vcc
	v_lshl_add_u64 v[126:127], v[126:127], 0, v[210:211]
	v_mad_i64_i32 v[134:135], s[6:7], v134, s79, v[170:171]
	s_waitcnt vmcnt(14)
	v_mfma_f32_16x16x32_bf16 v[202:205], v[50:53], v[42:45], v[142:145]
	v_lshl_add_u64 v[130:131], v[126:127], 0, s[20:21]
	v_add_co_u32_e32 v126, vcc, s80, v126
	s_nop 0
	v_add_u32_e32 v142, s8, v162
	v_lshl_add_u64 v[134:135], v[134:135], 0, s[0:1]
	v_mad_i64_i32 v[146:147], s[6:7], v142, s79, v[170:171]
	s_waitcnt vmcnt(13)
	v_mfma_f32_16x16x32_bf16 v[142:145], v[54:57], v[38:41], 0
	v_addc_co_u32_e32 v127, vcc, 0, v127, vcc
	v_lshl_add_u64 v[134:135], v[134:135], 0, v[210:211]
	v_lshl_add_u64 v[136:137], v[134:135], 0, s[20:21]
	v_add_co_u32_e32 v134, vcc, s80, v134
	v_lshl_add_u64 v[146:147], v[146:147], 0, s[0:1]
	s_nop 0
	v_addc_co_u32_e32 v135, vcc, 0, v135, vcc
	v_lshl_add_u64 v[146:147], v[146:147], 0, v[210:211]
	s_waitcnt vmcnt(12)
	v_mfma_f32_16x16x32_bf16 v[198:201], v[58:61], v[42:45], v[142:145]
	v_lshl_add_u64 v[150:151], v[146:147], 0, s[20:21]
	ds_read_b128 v[110:113], v254
	s_nop 0
	ds_read_b128 v[114:117], v254 offset:64
	v_add_co_u32_e32 v142, vcc, s80, v146
	ds_read_b128 v[118:121], v254 offset:2560
	s_nop 0
	ds_read_b128 v[122:125], v254 offset:2624
	v_addc_co_u32_e32 v143, vcc, 0, v147, vcc
	ds_read_b128 v[126:129], v254 offset:10240
	s_nop 0
	ds_read_b128 v[130:133], v254 offset:10304
	s_nop 0
	ds_read_b128 v[138:141], v254 offset:12800
	s_nop 0
	ds_read_b128 v[134:137], v254 offset:12864
	s_nop 0
	ds_read_b128 v[146:149], v254 offset:20480
	s_nop 0
	ds_read_b128 v[142:145], v254 offset:20544
	s_waitcnt vmcnt(21)
; #define LAS __attribute__((address_space(3)))
; __device__ __forceinline__ void mixC_mfma(const bf16* P, const float* rpb  , bf16* MIX, LAS unsigned char* lds, int bid, int G, int tid) {
;     ...
; #pragma unroll
;         for (int kt = 8; kt < 16; ++kt) { const bf16* kp = P + (size_t)(s0 + (rs + (kt >> 1)) * 64 + kcol0 + 16 * (kt & 1) + fr) * DIN + C_KC + h * 64 + fq * 8;
;             Kl[kt - 8][0] = *(const bf16x8*)kp; Kl[kt - 8][1] = *(const bf16x8*)(kp + 32); }
; #pragma unroll
;         for (int kt = 0; kt < 8; ++kt) { f32x4 z = {0.f, 0.f, 0.f, 0.f};
;             z = __builtin_amdgcn_mfma_f32_16x16x32_bf16(Kn[kt][0], Qn0, z, 0, 0, 0);
;             S[kt] = __builtin_amdgcn_mfma_f32_16x16x32_bf16(Kn[kt][1], Qn1, z, 0, 0, 0); }
;         const int d0 = kcol0 + 4 * fq - cs;
;         const LAS float* rpl = rp + h * 512 + (rs - r + 7) * 31 + (kcol0 + 4 * fq - c + 15);
;         float m1 = -1e30f;
; #pragma unroll
;         for (int kt = 0; kt < 8; ++kt)
; #pragma unroll
;             for (int t = 0; t < 4; ++t) {
;                 const bool ok = (unsigned)(d0 + 16 * (kt & 1) + t) < 16u;
;                 const float sv = ok ? S[kt][t] * (0.125f * L2E) + rpl[(kt >> 1) * 31 + 16 * (kt & 1) + t] : -1e30f;
;                 S[kt][t] = sv; m1 = fmaxf(m1, sv);
	v_mfma_f32_16x16x32_bf16 v[150:153], v[62:65], v[38:41], 0
	v_add_u32_e32 v154, s8, v172
	v_mad_i64_i32 v[154:155], s[6:7], v154, s79, v[170:171]
	s_waitcnt vmcnt(20)
	v_mfma_f32_16x16x32_bf16 v[194:197], v[66:69], v[42:45], v[150:153]
	s_addk_i32 s5, 0x1c0
	v_add_u32_e32 v162, s5, v162
	v_mad_i64_i32 v[162:163], s[6:7], v162, s79, v[170:171]
	s_nop 0
	v_lshl_add_u64 v[150:151], v[154:155], 0, s[0:1]
	v_lshl_add_u64 v[154:155], v[150:151], 0, v[210:211]
	s_waitcnt vmcnt(19)
	v_mfma_f32_16x16x32_bf16 v[150:153], v[70:73], v[38:41], 0
	v_lshl_add_u64 v[158:159], v[154:155], 0, s[20:21]
	v_add_co_u32_e32 v154, vcc, s80, v154
	s_waitcnt vmcnt(15)
	v_mfma_f32_16x16x32_bf16 v[166:169], v[86:89], v[38:41], 0
	v_addc_co_u32_e32 v155, vcc, 0, v155, vcc
	v_add_u32_e32 v217, s85, v212
	v_mfma_f32_16x16x32_bf16 v[190:193], v[74:77], v[42:45], v[150:153]
	ds_read_b128 v[154:157], v254 offset:23040
	s_nop 1
	ds_read_b128 v[150:153], v254 offset:23104
	v_sub_u32_e32 v215, v217, v209
	v_sub_u32_e32 v217, v217, v1
	v_mfma_f32_16x16x32_bf16 v[158:161], v[82:85], v[38:41], 0
	s_waitcnt vmcnt(16)
	v_mfma_f32_16x16x32_bf16 v[182:185], v[90:93], v[42:45], v[166:169]
	s_nop 2
	v_add_u32_e32 v166, s5, v172
	v_mfma_f32_16x16x32_bf16 v[186:189], v[78:81], v[42:45], v[158:161]
	v_mad_i64_i32 v[170:171], s[6:7], v166, s79, v[170:171]
	v_lshl_add_u64 v[170:171], v[170:171], 0, s[0:1]
	s_nop 0
	v_lshl_add_u64 v[158:159], v[162:163], 0, s[0:1]
	s_waitcnt vmcnt(15)
	v_mfma_f32_16x16x32_bf16 v[166:169], v[94:97], v[38:41], 0
	v_lshl_add_u64 v[158:159], v[158:159], 0, v[210:211]
	v_lshl_add_u64 v[160:161], v[158:159], 0, s[20:21]
	v_add_co_u32_e32 v158, vcc, s80, v158
	v_lshl_add_u64 v[170:171], v[170:171], 0, v[210:211]
	s_nop 0
	v_addc_co_u32_e32 v159, vcc, 0, v159, vcc
	s_waitcnt vmcnt(14)
	v_mfma_f32_16x16x32_bf16 v[178:181], v[98:101], v[42:45], v[166:169]
	ds_read_b128 v[162:165], v254 offset:30720
	s_nop 0
	ds_read_b128 v[158:161], v254 offset:30784
	v_add_co_u32_e32 v166, vcc, s80, v170
	v_lshl_add_u64 v[230:231], v[170:171], 0, s[20:21]
	s_nop 0
	v_addc_co_u32_e32 v167, vcc, 0, v171, vcc
	ds_read_b128 v[170:173], v254 offset:33280
	s_nop 0
	ds_read_b128 v[166:169], v254 offset:33344
	s_waitcnt vmcnt(17)
	v_mfma_f32_16x16x32_bf16 v[174:177], v[102:105], v[38:41], 0
	s_lshl_b32 s0, s4, 11
	s_sub_i32 s1, s86, s83
	s_add_i32 s0, s0, 0
	s_waitcnt vmcnt(16)
	v_mfma_f32_16x16x32_bf16 v[174:177], v[106:109], v[42:45], v[174:177]
	s_mulk_i32 s1, 0x7c
	s_add_i32 s0, s0, s1
	v_add_u32_e32 v230, 8, v215
	s_add_i32 s0, s0, 0x16800
	v_lshl_add_u32 v231, v217, 2, s0
	s_waitcnt lgkmcnt(0)
	ds_read_b32 v46, v231 offset:928
	ds_read_b32 v47, v231 offset:932
	ds_read_b32 v48, v231 offset:936
	ds_read_b32 v49, v231 offset:940
	ds_read_b32 v50, v231 offset:992
	ds_read_b32 v51, v231 offset:996
	ds_read_b32 v52, v231 offset:1000
	ds_read_b32 v53, v231 offset:1004
	ds_read_b32 v54, v231 offset:1052
	ds_read_b32 v55, v231 offset:1056
	ds_read_b32 v56, v231 offset:1060
	ds_read_b32 v57, v231 offset:1064
	ds_read_b32 v58, v231 offset:1116
	ds_read_b32 v59, v231 offset:1120
	ds_read_b32 v60, v231 offset:1124
	ds_read_b32 v61, v231 offset:1128
	v_cmp_gt_u32_e64 s[0:1], 16, v230
	v_mov_b32_e32 v217, 0xf149f2ca
	v_mov_b32_e32 v230, 0xf149f2ca
	s_and_saveexec_b64 s[4:5], s[0:1]
	s_cbranch_execz .LBB0_1385
	s_waitcnt lgkmcnt(0)
	v_fmamk_f32 v230, v202, 0x3e38aa3b, v46

; #define LAS __attribute__((address_space(3)))
; __device__ __forceinline__ void mixC_mfma(const bf16* P, const float* rpb  , bf16* MIX, LAS unsigned char* lds, int bid, int G, int tid) {
;     ...
; #pragma unroll
;         for (int i = 0; i < 9; ++i) { const int e = tid + i * NTHREADS; *(LAS v4u*)(Vs + (e >> 3) * VROW + (e & 7) * 16) = vpre[i]; }
;         __syncthreads();
;     ...
;         for (int kt = 8; kt < 16; ++kt) { f32x4 z = {0.f, 0.f, 0.f, 0.f};
;             z = __builtin_amdgcn_mfma_f32_16x16x32_bf16(Kl[kt - 8][0], Qn0, z, 0, 0, 0);
;             S[kt] = __builtin_amdgcn_mfma_f32_16x16x32_bf16(Kl[kt - 8][1], Qn1, z, 0, 0, 0); }
;         asm volatile("" ::: "memory");
.LBB0_1447:
	s_or_b64 exec, exec, s[26:27]
	s_waitcnt lgkmcnt(0)
	v_mfma_f32_16x16x32_bf16 v[110:113], v[110:113], v[38:41], 0
	s_mov_b32 s26, 0xf149f2ca
	s_add_i32 s12, s12, s68
	s_nop 0
	v_mfma_f32_16x16x32_bf16 v[178:181], v[114:117], v[42:45], v[110:113]
	v_max3_f32 v114, v230, s26, v217
	s_cmpk_gt_i32 s12, 0x8ff
	s_cselect_b64 s[26:27], -1, 0
	s_nop 0
	v_mfma_f32_16x16x32_bf16 v[110:113], v[118:121], v[38:41], 0
	s_and_b64 vcc, exec, s[26:27]
	s_nop 0
	v_mfma_f32_16x16x32_bf16 v[174:177], v[122:125], v[42:45], v[110:113]
	s_nop 0
	v_mfma_f32_16x16x32_bf16 v[110:113], v[126:129], v[38:41], 0
	s_nop 0
	v_mfma_f32_16x16x32_bf16 v[130:133], v[130:133], v[42:45], v[110:113]
	s_nop 0
	v_mfma_f32_16x16x32_bf16 v[110:113], v[138:141], v[38:41], 0
	s_nop 0
	v_mfma_f32_16x16x32_bf16 v[126:129], v[134:137], v[42:45], v[110:113]
	s_nop 5
	v_max3_f32 v110, v114, v203, v202
	v_max3_f32 v110, v110, v205, v204
	v_max3_f32 v114, v110, v199, v198
	s_nop 0
	v_mfma_f32_16x16x32_bf16 v[110:113], v[146:149], v[38:41], 0
	v_max3_f32 v114, v114, v201, v200
	v_max3_f32 v114, v114, v195, v194
	v_max3_f32 v114, v114, v197, v196
	s_nop 0
	v_mfma_f32_16x16x32_bf16 v[122:125], v[142:145], v[42:45], v[110:113]
	s_nop 2
	v_max3_f32 v110, v114, v191, v190
	v_max3_f32 v110, v110, v193, v192
	v_max3_f32 v114, v110, v187, v186
	s_nop 0
	v_mfma_f32_16x16x32_bf16 v[110:113], v[154:157], v[38:41], 0
	v_max3_f32 v114, v114, v189, v188
	v_max3_f32 v114, v114, v183, v182
	v_max3_f32 v114, v114, v185, v184
	s_nop 0
	v_mfma_f32_16x16x32_bf16 v[118:121], v[150:153], v[42:45], v[110:113]
	s_nop 2
	v_max3_f32 v110, v114, v233, v232
	v_max3_f32 v110, v110, v235, v234
	v_max3_f32 v114, v110, v237, v236
	ds_bpermute_b32 v115, v219, v114
	s_nop 0
	v_mfma_f32_16x16x32_bf16 v[110:113], v[162:165], v[38:41], 0
	s_waitcnt lgkmcnt(0)
	v_max_f32_e32 v115, v115, v115
	v_max_f32_e32 v134, v114, v115
	s_nop 0
	v_mfma_f32_16x16x32_bf16 v[114:117], v[158:161], v[42:45], v[110:113]
	ds_bpermute_b32 v135, v220, v134
	s_nop 0
	v_mfma_f32_16x16x32_bf16 v[110:113], v[170:173], v[38:41], 0
	s_nop 0
	v_mfma_f32_16x16x32_bf16 v[110:113], v[166:169], v[42:45], v[110:113]
	s_waitcnt vmcnt(0)
	s_waitcnt lgkmcnt(0)
	s_barrier
	ds_write_b128 v223, v[2:5]
	ds_write_b128 v226, v[6:9]
	ds_write_b128 v223, v[10:13] offset:20480
	ds_write_b128 v227, v[14:17]
	ds_write_b128 v223, v[18:21] offset:40960
	ds_write_b128 v228, v[22:25]
	ds_write_b128 v223, v[26:29] offset:61440
	ds_write_b128 v229, v[30:33]
	ds_write_b128 v224, v[34:37]
	s_waitcnt lgkmcnt(0)
	s_barrier
	ds_read_b32 v239, v231 offset:1424
	ds_read_b32 v240, v231 offset:1428
	ds_read_b32 v241, v231 offset:1432
	ds_read_b32 v242, v231 offset:1436
	ds_read_b32 v243, v231 offset:1488
	ds_read_b32 v244, v231 offset:1492
	ds_read_b32 v245, v231 offset:1496
	ds_read_b32 v246, v231 offset:1500
	ds_read_b32 v247, v231 offset:1548
	ds_read_b32 v248, v231 offset:1552
	ds_read_b32 v249, v231 offset:1556
	ds_read_b32 v250, v231 offset:1560
	ds_read_b32 v251, v231 offset:1612
	ds_read_b32 v252, v231 offset:1616
	ds_read_b32 v253, v231 offset:1620
	ds_read_b32 v254, v231 offset:1624
	s_cbranch_vccz .LBB0_1511
	v_mov_b32_e32 v138, 0xf149f2ca
	v_mov_b32_e32 v139, 0xf149f2ca
	s_and_saveexec_b64 s[40:41], s[0:1]
	s_cbranch_execnz .LBB0_1517

; __device__ __forceinline__ void seq_of(int row, int& s0, int& T) { if (row < MP) { s0 = row & ~2047; T = 2048; } else { s0 = MP + ((row - MP) & ~4095); T = 4096; } }
; __device__ __forceinline__ void c_prefetch(const bf16* P, int un, int tid, int wave, int fr, int fq, v4u (&vpre)[9], bf16x8& Q0, bf16x8& Q1, bf16x8 (&K)[8][2]) {
;     const int h = un / (M / 128), blk = un - h * (M / 128), row0 = blk * 128; int s0, T; seq_of(row0, s0, T);
;     const int rows = T >> 6, rf = (row0 - s0) >> 6;
;     int R0 = rf - 4; R0 = R0 < 0 ? 0 : R0; R0 = R0 > rows - 8 ? rows - 8 : R0;
; #pragma unroll
;     for (int i = 0; i < 9; ++i) { const int e = tid + i * NTHREADS, key = e >> 3, chunk = e & 7; int gr = R0 + (key >> 6); gr = gr > rows - 1 ? rows - 1 : gr;
;         vpre[i] = *(const v4u*)(P + (size_t)(s0 + gr * 64 + (key & 63)) * DIN + C_VC + h * 64 + chunk * 8); }
.LBB0_1511:
	s_mul_hi_i32 s29, s12, 0x2aaaaaab
	s_lshr_b32 s31, s29, 31
	s_ashr_i32 s29, s29, 5
	s_add_i32 s40, s29, s31
	s_mul_i32 s29, s40, 0xffffff40
	s_mul_i32 s31, s40, 0xffffa000
	s_add_i32 s35, s56, s57
	s_add_i32 s29, s12, s29
	s_add_i32 s31, s35, s31
	s_cmpk_lt_i32 s29, 0x80
	s_cselect_b32 s29, s78, 0x7ffff000
	s_cselect_b32 s41, 32, 64
	s_and_b32 s29, s29, s31
	s_mul_i32 s31, s40, 0x6000
	s_add_i32 s31, s29, s31
	s_sub_i32 s31, s35, s31
	s_ashr_i32 s31, s31, 6
	s_max_i32 s35, s31, 4
	s_add_i32 s42, s35, -4
	s_add_i32 s35, s41, -8
	s_min_u32 s42, s42, s35
	v_add_u32_e32 v36, s42, v207
	s_add_i32 s50, s41, -1
	v_or_b32_e32 v37, s29, v221
	s_lshl_b32 s40, s40, 6
	v_min_u32_e32 v2, s50, v36
	s_ashr_i32 s41, s40, 31
	v_lshl_add_u32 v2, v2, 6, v37
	v_mov_b64_e32 v[34:35], s[74:75]
	v_add_u32_e32 v4, 1, v36
	v_mad_i64_i32 v[2:3], s[42:43], v2, s79, v[34:35]
	s_lshl_b64 s[40:41], s[40:41], 1
	v_min_u32_e32 v4, s50, v4
	v_lshl_add_u64 v[2:3], v[2:3], 0, s[40:41]
	v_mov_b32_e32 v215, v211
	v_lshl_add_u32 v4, v4, 6, v37
	v_add_u32_e32 v10, 2, v36
	v_lshl_add_u64 v[2:3], v[2:3], 0, v[214:215]
	v_mad_i64_i32 v[4:5], s[42:43], v4, s79, v[34:35]
	v_min_u32_e32 v10, s50, v10
	v_add_co_u32_e32 v2, vcc, s80, v2
	v_lshl_add_u64 v[4:5], v[4:5], 0, s[40:41]
	v_lshl_add_u32 v10, v10, 6, v37
	v_add_u32_e32 v12, 3, v36
	v_addc_co_u32_e32 v3, vcc, 0, v3, vcc
	v_lshl_add_u64 v[4:5], v[4:5], 0, v[214:215]
	v_mad_i64_i32 v[10:11], s[42:43], v10, s79, v[34:35]
	v_min_u32_e32 v12, s50, v12
	v_add_co_u32_e32 v6, vcc, s80, v4
	v_lshl_add_u64 v[10:11], v[10:11], 0, s[40:41]
	v_lshl_add_u32 v12, v12, 6, v37
	v_add_u32_e32 v18, 4, v36
	v_addc_co_u32_e32 v7, vcc, 0, v5, vcc
	v_lshl_add_u64 v[10:11], v[10:11], 0, v[214:215]
	v_mad_i64_i32 v[12:13], s[42:43], v12, s79, v[34:35]
	v_min_u32_e32 v18, s50, v18
	v_add_co_u32_e32 v10, vcc, s80, v10
	v_lshl_add_u64 v[12:13], v[12:13], 0, s[40:41]
	v_lshl_add_u32 v18, v18, 6, v37
	v_add_u32_e32 v20, 5, v36
	v_addc_co_u32_e32 v11, vcc, 0, v11, vcc
	v_lshl_add_u64 v[12:13], v[12:13], 0, v[214:215]
	v_mad_i64_i32 v[18:19], s[42:43], v18, s79, v[34:35]
	v_min_u32_e32 v20, s50, v20
	v_add_co_u32_e32 v14, vcc, s80, v12
	v_lshl_add_u64 v[18:19], v[18:19], 0, s[40:41]
	v_lshl_add_u32 v20, v20, 6, v37
	v_add_u32_e32 v26, 6, v36
	v_addc_co_u32_e32 v15, vcc, 0, v13, vcc
	v_lshl_add_u64 v[18:19], v[18:19], 0, v[214:215]
	v_mad_i64_i32 v[20:21], s[42:43], v20, s79, v[34:35]
	v_min_u32_e32 v26, s50, v26
	v_add_co_u32_e32 v18, vcc, s80, v18
	v_lshl_add_u64 v[20:21], v[20:21], 0, s[40:41]
	v_lshl_add_u32 v26, v26, 6, v37
	v_add_u32_e32 v28, 7, v36
	v_addc_co_u32_e32 v19, vcc, 0, v19, vcc
	v_lshl_add_u64 v[20:21], v[20:21], 0, v[214:215]
	v_mad_i64_i32 v[26:27], s[42:43], v26, s79, v[34:35]
	v_min_u32_e32 v28, s50, v28
	v_add_co_u32_e32 v22, vcc, s80, v20
	v_lshl_add_u64 v[26:27], v[26:27], 0, s[40:41]
	v_lshl_add_u32 v28, v28, 6, v37
	v_add_u32_e32 v36, 8, v36
	v_addc_co_u32_e32 v23, vcc, 0, v21, vcc
	v_lshl_add_u64 v[26:27], v[26:27], 0, v[214:215]
	v_mad_i64_i32 v[28:29], s[42:43], v28, s79, v[34:35]
	v_min_u32_e32 v36, s50, v36
	v_add_co_u32_e32 v26, vcc, s80, v26
	v_lshl_add_u64 v[28:29], v[28:29], 0, s[40:41]
	v_lshl_add_u32 v36, v36, 6, v37
	v_addc_co_u32_e32 v27, vcc, 0, v27, vcc
	v_lshl_add_u64 v[28:29], v[28:29], 0, v[214:215]
	v_mad_i64_i32 v[34:35], s[42:43], v36, s79, v[34:35]
	v_add_co_u32_e32 v30, vcc, s80, v28
	v_lshl_add_u64 v[34:35], v[34:35], 0, s[40:41]
	s_nop 0
	v_addc_co_u32_e32 v31, vcc, 0, v29, vcc
	v_lshl_add_u64 v[34:35], v[34:35], 0, v[214:215]
	v_add_co_u32_e32 v34, vcc, 0x2000, v34
	v_mov_b32_e32 v100, v2
	v_mov_b32_e32 v101, v3
	global_load_dwordx4 v[2:5], v[2:3], off
	s_nop 0
	global_load_dwordx4 v[6:9], v[6:7], off
	v_addc_co_u32_e32 v35, vcc, 0, v35, vcc
	global_load_dwordx4 v[10:13], v[10:11], off
	s_nop 0
	global_load_dwordx4 v[14:17], v[14:15], off
	s_nop 0
	global_load_dwordx4 v[18:21], v[18:19], off
	s_nop 0
	global_load_dwordx4 v[22:25], v[22:23], off
	s_nop 0
	global_load_dwordx4 v[26:29], v[26:27], off
	s_nop 0
	global_load_dwordx4 v[30:33], v[30:31], off
	s_cmp_lt_i32 s33, 1
	v_mov_b32_e32 v108, v34
	v_mov_b32_e32 v109, v35
	global_load_dwordx4 v[34:37], v[34:35], off
	s_mov_b32 s42, s33
	s_cbranch_scc1 .LBB0_1516
	s_cmp_eq_u32 s33, 1
	s_mov_b64 s[42:43], -1
	s_cbranch_scc1 .LBB0_1514
	s_mov_b64 s[42:43], 0

; __device__ __forceinline__ void c_prefetch(const bf16* P, int un, int tid, int wave, int fr, int fq, v4u (&vpre)[9], bf16x8& Q0, bf16x8& Q1, bf16x8 (&K)[8][2]) {
;     ...
;     const int r = rf + (wave >> 2), j = wave & 3;
;     int rs = r - 4; rs = rs < 0 ? 0 : rs; rs = rs > rows - 8 ? rows - 8 : rs;
;     const int kcol0 = j == 0 ? 0 : (j == 1 ? 8 : (j == 2 ? 24 : 32));
;     { const bf16* qp = P + (size_t)(s0 + r * 64 + 16 * j + fr) * DIN + C_QC + h * 64 + fq * 8; Q0 = *(const bf16x8*)qp; Q1 = *(const bf16x8*)(qp + 32); }
; #pragma unroll
;     for (int kt = 0; kt < 8; ++kt) { const bf16* kp = P + (size_t)(s0 + (rs + (kt >> 1)) * 64 + kcol0 + 16 * (kt & 1) + fr) * DIN + C_KC + h * 64 + fq * 8;
;         K[kt][0] = *(const bf16x8*)kp; K[kt][1] = *(const bf16x8*)(kp + 32); }
.LBB0_1516:
	s_add_i32 s31, s31, s13
	s_max_i32 s43, s31, 4
	s_lshl_b32 s31, s31, 6
	s_add_i32 s43, s43, -4
	s_add_i32 s31, s31, s29
	s_min_u32 s35, s43, s35
	v_or_b32_e32 v38, s31, v1
	v_mov_b64_e32 v[102:103], s[74:75]
	v_or_b32_e32 v46, s29, v213
	v_mad_i64_i32 v[38:39], s[88:89], v38, s79, v[102:103]
	v_add_u32_e32 v94, s42, v46
	s_lshl_b32 s29, s35, 6
	v_lshl_add_u64 v[38:39], v[38:39], 0, s[40:41]
	v_add_u32_e32 v46, s29, v94
	v_lshl_add_u64 v[38:39], v[38:39], 0, v[210:211]
	v_mad_i64_i32 v[46:47], s[42:43], v46, s79, v[102:103]
	v_add_u32_e32 v104, 16, v94
	v_lshl_add_u64 v[42:43], v[38:39], 0, s[22:23]
	v_add_co_u32_e32 v38, vcc, 0x1000, v38
	v_lshl_add_u64 v[46:47], v[46:47], 0, s[40:41]
	v_add_u32_e32 v54, s29, v104
	v_addc_co_u32_e32 v39, vcc, 0, v39, vcc
	v_lshl_add_u64 v[46:47], v[46:47], 0, v[210:211]
	v_mad_i64_i32 v[54:55], s[42:43], v54, s79, v[102:103]
	s_add_i32 s31, s29, 64
	v_lshl_add_u64 v[50:51], v[46:47], 0, s[20:21]
	v_add_co_u32_e32 v46, vcc, s80, v46
	v_lshl_add_u64 v[54:55], v[54:55], 0, s[40:41]
	v_add_u32_e32 v62, s31, v94
	v_addc_co_u32_e32 v47, vcc, 0, v47, vcc
	v_lshl_add_u64 v[54:55], v[54:55], 0, v[210:211]
	v_mad_i64_i32 v[62:63], s[42:43], v62, s79, v[102:103]
	v_lshl_add_u64 v[58:59], v[54:55], 0, s[20:21]
	v_add_co_u32_e32 v54, vcc, s80, v54
	v_lshl_add_u64 v[62:63], v[62:63], 0, s[40:41]
	v_add_u32_e32 v70, s31, v104
	v_addc_co_u32_e32 v55, vcc, 0, v55, vcc
	v_lshl_add_u64 v[62:63], v[62:63], 0, v[210:211]
	v_mad_i64_i32 v[70:71], s[42:43], v70, s79, v[102:103]
	s_add_i32 s31, s29, 0x80
	v_lshl_add_u64 v[66:67], v[62:63], 0, s[20:21]
	v_add_co_u32_e32 v62, vcc, s80, v62
	v_lshl_add_u64 v[70:71], v[70:71], 0, s[40:41]
	v_add_u32_e32 v78, s31, v94
	v_addc_co_u32_e32 v63, vcc, 0, v63, vcc
	v_lshl_add_u64 v[70:71], v[70:71], 0, v[210:211]
	v_mad_i64_i32 v[78:79], s[42:43], v78, s79, v[102:103]
	v_lshl_add_u64 v[74:75], v[70:71], 0, s[20:21]
	v_add_co_u32_e32 v70, vcc, s80, v70
	v_lshl_add_u64 v[78:79], v[78:79], 0, s[40:41]
	v_add_u32_e32 v86, s31, v104
	v_addc_co_u32_e32 v71, vcc, 0, v71, vcc
	v_lshl_add_u64 v[78:79], v[78:79], 0, v[210:211]
	v_mad_i64_i32 v[86:87], s[42:43], v86, s79, v[102:103]
	s_addk_i32 s29, 0xc0
	v_lshl_add_u64 v[80:81], v[78:79], 0, s[20:21]
	v_add_co_u32_e32 v78, vcc, s80, v78
	v_lshl_add_u64 v[86:87], v[86:87], 0, s[40:41]
	v_add_u32_e32 v94, s29, v94
	v_addc_co_u32_e32 v79, vcc, 0, v79, vcc
	v_lshl_add_u64 v[86:87], v[86:87], 0, v[210:211]
	v_mad_i64_i32 v[94:95], s[42:43], v94, s79, v[102:103]
	v_lshl_add_u64 v[90:91], v[86:87], 0, s[20:21]
	v_add_co_u32_e32 v86, vcc, s80, v86
	v_lshl_add_u64 v[94:95], v[94:95], 0, s[40:41]
	v_add_u32_e32 v104, s29, v104
	v_addc_co_u32_e32 v87, vcc, 0, v87, vcc
	v_lshl_add_u64 v[94:95], v[94:95], 0, v[210:211]
	v_mad_i64_i32 v[102:103], s[42:43], v104, s79, v[102:103]
	v_lshl_add_u64 v[98:99], v[94:95], 0, s[20:21]
	v_add_co_u32_e32 v94, vcc, s80, v94
	v_lshl_add_u64 v[102:103], v[102:103], 0, s[40:41]
	s_nop 0
	v_addc_co_u32_e32 v95, vcc, 0, v95, vcc
	v_lshl_add_u64 v[102:103], v[102:103], 0, v[210:211]
	v_lshl_add_u64 v[106:107], v[102:103], 0, s[20:21]
	v_add_co_u32_e32 v102, vcc, 0x2000, v102
	global_load_dwordx4 v[38:41], v[38:39], off offset:2560
	s_nop 0
	global_load_dwordx4 v[42:45], v[42:43], off offset:64
	v_addc_co_u32_e32 v103, vcc, 0, v103, vcc
	s_nop 0
	s_nop 0
	s_nop 0
	s_nop 0
	s_nop 0
	s_nop 0
	s_nop 0
	s_nop 0
	s_nop 0
	s_nop 0
	s_nop 0
	s_nop 0
	s_nop 0
	s_nop 0
	s_nop 0
	s_nop 0
	s_nop 0
	s_nop 0
	s_nop 0
	s_nop 0
	s_nop 0
	s_nop 0
	s_nop 0
	s_nop 0
	s_nop 0
	s_nop 0
	s_nop 0
	s_nop 0
	s_nop 0
	s_nop 0
	s_nop 0
	v_mov_b32_e32 v138, 0xf149f2ca
	v_mov_b32_e32 v139, 0xf149f2ca
	s_and_saveexec_b64 s[40:41], s[0:1]
	s_cbranch_execz .LBB0_1449
